# attention loops: precomputed DMA/LDS addresses, K-fragment LDS reads triple-buffered with counted lgkmcnt (both layers)
# speedup vs baseline: 1.0168x; 1.0168x over previous
.LBB0_449:
	s_lshl_b32 s0, s38, 1
	s_and_b32 s0, s0, 14
	s_ashr_i32 s34, s38, 7
	s_add_i32 s56, s0, s34
	s_ashr_i32 s57, s56, 31
	s_lshl_b32 s0, s38, 5
	s_lshl_b64 s[2:3], s[56:57], 12
	s_and_b32 s39, s0, 0xf00
	s_or_b32 s0, s2, s39
	s_mul_i32 s2, s3, 0x180
	s_mul_hi_u32 s3, s0, 0x180
	s_and_b32 s1, s21, 14
	s_add_i32 s3, s3, s2
	s_mulk_i32 s0, 0x180
	v_mov_b32_e32 v68, v166
	s_add_u32 s40, s7, s0
	s_addc_u32 s41, s14, s3
	v_ashrrev_i32_e32 v2, 6, v68
	s_mul_i32 s2, s56, 0x198000
	v_and_b32_e32 v168, 31, v68
	v_lshlrev_b32_e32 v150, 5, v2
	s_mul_hi_i32 s0, s56, 0x198000
	s_add_u32 s4, s15, s2
	v_bfe_u32 v169, v68, 5, 1
	v_or_b32_e32 v3, v150, v168
	v_mov_b64_e32 v[0:1], s[40:41]
	s_addc_u32 s5, s16, s0
	s_mul_i32 s2, s56, 0x110000
	v_mad_i64_i32 v[0:1], s[40:41], v3, s29, v[0:1]
	v_lshlrev_b32_e32 v152, 4, v169
	v_mov_b32_e32 v153, v149
	s_mul_hi_i32 s0, s56, 0x110000
	s_add_u32 s2, s17, s2
	v_lshl_add_u64 v[0:1], v[0:1], 0, v[152:153]
	s_addc_u32 s3, s20, s0
	global_load_dwordx4 v[140:143], v[0:1], off
	global_load_dwordx4 v[136:139], v[0:1], off offset:32
	global_load_dwordx4 v[132:135], v[0:1], off offset:64
	global_load_dwordx4 v[128:131], v[0:1], off offset:96
	global_load_dwordx4 v[124:127], v[0:1], off offset:128
	global_load_dwordx4 v[120:123], v[0:1], off offset:160
	global_load_dwordx4 v[116:119], v[0:1], off offset:192
	global_load_dwordx4 v[112:115], v[0:1], off offset:224
	global_load_dwordx4 v[108:111], v[0:1], off offset:256
	global_load_dwordx4 v[104:107], v[0:1], off offset:288
	global_load_dwordx4 v[100:103], v[0:1], off offset:320
	global_load_dwordx4 v[96:99], v[0:1], off offset:352
	v_readfirstlane_b32 s0, v2
	v_mov_b32_e32 v0, v166
	s_lshl_b32 s40, s0, 10
	s_cmp_lg_u32 0, -1
	v_mul_hi_i32 v1, v0, s31
	v_lshrrev_b32_e32 v2, 31, v1
	v_ashrrev_i32_e32 v1, 2, v1
	s_cselect_b32 s41, 0, 0
	v_add_u32_e32 v1, v1, v2
	s_add_i32 s41, s41, s40
	v_mul_lo_u32 v2, v1, s33
	v_mul_lo_u32 v3, v1, s29
	v_lshlrev_b32_e32 v1, 3, v1
	s_add_i32 s42, s41, 0xc000
	v_add_lshl_u32 v2, v2, v0, 4
	v_and_b32_e32 v1, 0x70, v1
	v_xad_u32 v1, v2, v1, v3
	s_mov_b32 m0, s42
	s_add_i32 s43, s41, 0xe000
	v_mov_b32_e32 v203, v1
	global_load_lds_dwordx4 v1, s[4:5]
	v_add_u32_e32 v1, 0x200, v0
	v_mul_hi_i32 v2, v1, s31
	v_lshrrev_b32_e32 v3, 31, v2
	v_ashrrev_i32_e32 v2, 2, v2
	v_add_u32_e32 v2, v2, v3
	v_mul_lo_u32 v3, v2, s33
	v_add_lshl_u32 v1, v3, v1, 4
	v_mul_lo_u32 v3, v2, s29
	v_lshlrev_b32_e32 v2, 3, v2
	v_and_b32_e32 v2, 0x70, v2
	v_xad_u32 v1, v1, v2, v3
	s_mov_b32 m0, s43
	s_mov_b32 s68, 0
	v_mov_b32_e32 v204, v1
	global_load_lds_dwordx4 v1, s[4:5]
	v_add_u32_e32 v1, 0x400, v0
	v_mul_hi_i32 v2, v1, s31
	v_lshrrev_b32_e32 v3, 31, v2
	v_ashrrev_i32_e32 v2, 2, v2
	v_add_u32_e32 v2, v2, v3
	v_mul_lo_u32 v3, v2, s33
	v_add_lshl_u32 v1, v3, v1, 4
	v_mul_lo_u32 v3, v2, s29
	v_lshlrev_b32_e32 v2, 3, v2
	v_and_b32_e32 v2, 0x70, v2
	v_xad_u32 v1, v1, v2, v3
	s_add_i32 m0, s41, 0x10000
	v_bfe_u32 v2, v0, 2, 2
	v_lshrrev_b32_e32 v3, 1, v0
	v_mov_b32_e32 v205, v1
	global_load_lds_dwordx4 v1, s[4:5]
	v_lshlrev_b32_e32 v1, 4, v0
	v_and_or_b32 v2, v3, 8, v2
	v_lshlrev_b32_e32 v3, 1, v0
	v_bfe_i32 v0, v0, 4, 24
	v_and_b32_e32 v4, 0xfffff0, v0
	v_lshrrev_b32_e32 v0, 1, v0
	v_and_b32_e32 v3, 0xc0, v3
	v_and_b32_e32 v0, 4, v0
	v_and_or_b32 v3, v1, 48, v3
	v_or3_b32 v0, v4, v0, v2
	v_lshl_or_b32 v0, v0, 8, v3
	s_mov_b32 m0, s41
	s_mov_b32 s69, s68
	v_mov_b32_e32 v206, v0
	global_load_lds_dwordx4 v0, s[2:3]
	v_add_u32_e32 v0, 0x2000, v1
	v_ashrrev_i32_e32 v0, 8, v0
	v_and_b32_e32 v1, 0xfffff0, v0
	v_lshrrev_b32_e32 v0, 1, v0
	v_and_b32_e32 v0, 4, v0
	v_or3_b32 v0, v1, v0, v2
	v_lshl_or_b32 v0, v0, 8, v3
	s_add_i32 m0, s41, 0x2000
	s_add_u32 s4, s4, 0x6000
	v_mov_b32_e32 v207, v0
	global_load_lds_dwordx4 v0, s[2:3]
	v_mov_b32_e32 v0, v166
	s_waitcnt vmcnt(0)
	s_waitcnt vmcnt(0) lgkmcnt(0)
	s_barrier
	s_addc_u32 s5, s5, 0
	v_mul_hi_i32 v1, v0, s31
	v_lshrrev_b32_e32 v2, 31, v1
	v_ashrrev_i32_e32 v1, 2, v1
	v_add_u32_e32 v1, v1, v2
	v_mul_lo_u32 v2, v1, s33
	v_mul_lo_u32 v3, v1, s29
	v_lshlrev_b32_e32 v1, 3, v1
	v_add_lshl_u32 v2, v2, v0, 4
	v_and_b32_e32 v1, 0x70, v1
	s_add_i32 m0, s41, 0x12000
	v_xad_u32 v1, v2, v1, v3
	global_load_lds_dwordx4 v1, s[4:5]
	v_add_u32_e32 v1, 0x200, v0
	v_mul_hi_i32 v2, v1, s31
	v_lshrrev_b32_e32 v3, 31, v2
	v_ashrrev_i32_e32 v2, 2, v2
	v_add_u32_e32 v2, v2, v3
	v_mul_lo_u32 v3, v2, s33
	v_add_lshl_u32 v1, v3, v1, 4
	v_mul_lo_u32 v3, v2, s29
	v_lshlrev_b32_e32 v2, 3, v2
	v_and_b32_e32 v2, 0x70, v2
	v_xad_u32 v1, v1, v2, v3
	s_add_i32 m0, s41, 0x14000
	s_mov_b32 s70, s68
	global_load_lds_dwordx4 v1, s[4:5]
	v_add_u32_e32 v1, 0x400, v0
	v_mul_hi_i32 v2, v1, s31
	v_lshrrev_b32_e32 v3, 31, v2
	v_ashrrev_i32_e32 v2, 2, v2
	v_add_u32_e32 v2, v2, v3
	v_mul_lo_u32 v3, v2, s33
	v_add_lshl_u32 v1, v3, v1, 4
	v_mul_lo_u32 v3, v2, s29
	v_lshlrev_b32_e32 v2, 3, v2
	v_and_b32_e32 v2, 0x70, v2
	v_xad_u32 v1, v1, v2, v3
	s_add_i32 m0, s41, 0x16000
	v_bfe_u32 v2, v0, 2, 2
	v_lshrrev_b32_e32 v3, 1, v0
	global_load_lds_dwordx4 v1, s[4:5]
	v_lshlrev_b32_e32 v1, 4, v0
	v_and_or_b32 v2, v3, 8, v2
	v_lshlrev_b32_e32 v3, 1, v0
	v_bfe_i32 v0, v0, 4, 24
	v_and_b32_e32 v4, 0xfffff0, v0
	v_lshrrev_b32_e32 v0, 1, v0
	v_and_b32_e32 v3, 0xc0, v3
	v_and_b32_e32 v0, 4, v0
	s_add_u32 s2, s2, 0x4000
	v_and_or_b32 v3, v1, 48, v3
	v_or3_b32 v0, v4, v0, v2
	s_addc_u32 s3, s3, 0
	s_add_i32 m0, s41, 0x4000
	v_lshl_or_b32 v0, v0, 8, v3
	global_load_lds_dwordx4 v0, s[2:3]
	v_add_u32_e32 v0, 0x2000, v1
	v_ashrrev_i32_e32 v0, 8, v0
	v_and_b32_e32 v1, 0xfffff0, v0
	v_lshrrev_b32_e32 v0, 1, v0
	v_and_b32_e32 v0, 4, v0
	v_or3_b32 v0, v1, v0, v2
	v_lshl_or_b32 v0, v0, 8, v3
	s_add_i32 m0, s41, 0x6000
	s_mov_b32 s71, s68
	global_load_lds_dwordx4 v0, s[2:3]
	v_mov_b32_e32 v0, v166
	s_mov_b32 s72, s68
	v_and_b32_e32 v1, 31, v0
	v_lshlrev_b32_e32 v2, 3, v0
	v_lshrrev_b32_e32 v0, 1, v0
	v_and_b32_e32 v56, 0x70, v2
	v_mad_u32_u24 v57, v1, s29, 0
	v_and_b32_e32 v58, 16, v0
	v_xad_u32 v69, v58, v56, v57
	ds_read_b128 v[0:3], v69 offset:49152
	ds_read_b128 v[4:7], v69 offset:49280
	s_waitcnt lgkmcnt(0)
	v_mfma_f32_32x32x16_bf16 v[16:31], v[0:3], v[140:143], 0
	ds_read_b128 v[0:3], v69 offset:61440
	v_or_b32_e32 v8, 32, v58
	v_xad_u32 v70, v8, v56, v57
	ds_read_b128 v[8:11], v69 offset:49408
	v_or_b32_e32 v48, 64, v58
	v_xad_u32 v71, v48, v56, v57
	v_or_b32_e32 v58, 0x60, v58
	s_waitcnt lgkmcnt(0)
	v_mfma_f32_32x32x16_bf16 v[32:47], v[0:3], v[140:143], 0
	ds_read_b128 v[0:3], v70 offset:49152
	ds_read_b128 v[12:15], v70 offset:49280
	ds_read_b128 v[48:51], v70 offset:49408
	v_xad_u32 v72, v58, v56, v57
	s_mov_b32 s73, s68
	s_mov_b32 s74, s68
	s_mov_b32 s75, s68
	s_mov_b32 s76, s68
	s_waitcnt lgkmcnt(0)
	v_mfma_f32_32x32x16_bf16 v[16:31], v[0:3], v[136:139], v[16:31]
	ds_read_b128 v[0:3], v70 offset:61440
	s_mov_b32 s77, s68
	s_mov_b32 s78, s68
	s_mov_b32 s79, s68
	s_mov_b32 s80, s68
	s_mov_b32 s81, s68
	s_mov_b32 s82, s68
	s_waitcnt lgkmcnt(0)
	v_mfma_f32_32x32x16_bf16 v[32:47], v[0:3], v[136:139], v[32:47]
	ds_read_b128 v[0:3], v71 offset:49152
	ds_read_b128 v[52:55], v71 offset:49280
	ds_read_b128 v[56:59], v71 offset:49408
	s_mov_b32 s83, s68
	s_mov_b32 s0, -1
	v_cmp_eq_u32_e64 s[2:3], 0, v169
	s_movk_i32 s49, 0x4000
	s_mov_b32 s50, 0x8000
	s_waitcnt lgkmcnt(0)
	v_mfma_f32_32x32x16_bf16 v[16:31], v[0:3], v[132:135], v[16:31]
	ds_read_b128 v[0:3], v71 offset:61440
	v_mov_b32_e32 v170, v149
	s_waitcnt lgkmcnt(0)
	v_mfma_f32_32x32x16_bf16 v[32:47], v[0:3], v[132:135], v[32:47]
	ds_read_b128 v[0:3], v72 offset:49152
	ds_read_b128 v[60:63], v72 offset:49280
	s_waitcnt lgkmcnt(0)
	v_mfma_f32_32x32x16_bf16 v[16:31], v[0:3], v[128:131], v[16:31]
	ds_read_b128 v[0:3], v72 offset:61440
	ds_read_b128 v[64:67], v72 offset:49408
	v_mfma_f32_32x32x16_bf16 v[16:31], v[4:7], v[124:127], v[16:31]
	s_waitcnt lgkmcnt(0)
	v_mfma_f32_32x32x16_bf16 v[32:47], v[0:3], v[128:131], v[32:47]
	ds_read_b128 v[0:3], v69 offset:61568
	ds_read_b128 v[4:7], v69 offset:61696
	v_mfma_f32_32x32x16_bf16 v[16:31], v[12:15], v[120:123], v[16:31]
	s_waitcnt lgkmcnt(0)
	v_mfma_f32_32x32x16_bf16 v[32:47], v[0:3], v[124:127], v[32:47]
	ds_read_b128 v[0:3], v70 offset:61568
	ds_read_b128 v[12:15], v70 offset:61696
	v_mfma_f32_32x32x16_bf16 v[16:31], v[52:55], v[116:119], v[16:31]
	s_waitcnt lgkmcnt(0)
	v_mfma_f32_32x32x16_bf16 v[32:47], v[0:3], v[120:123], v[32:47]
	ds_read_b128 v[0:3], v71 offset:61568
	ds_read_b128 v[52:55], v71 offset:61696
	v_mfma_f32_32x32x16_bf16 v[16:31], v[60:63], v[112:115], v[16:31]
	s_waitcnt lgkmcnt(0)
	v_mfma_f32_32x32x16_bf16 v[32:47], v[0:3], v[116:119], v[32:47]
	ds_read_b128 v[0:3], v72 offset:61568
	ds_read_b128 v[60:63], v72 offset:61696
	s_waitcnt vmcnt(0)
	s_waitcnt vmcnt(0) lgkmcnt(0)
	s_barrier
	v_mfma_f32_32x32x16_bf16 v[16:31], v[8:11], v[108:111], v[16:31]
	v_mfma_f32_32x32x16_bf16 v[32:47], v[0:3], v[112:115], v[32:47]
	v_and_b32_e32 v0, 0x3fffffc0, v68
	v_lshl_add_u32 v151, v0, 2, s30
	v_lshl_add_u32 v153, v168, 2, v151
	v_mfma_f32_32x32x16_bf16 v[16:31], v[48:51], v[104:107], v[16:31]
	v_mfma_f32_32x32x16_bf16 v[32:47], v[4:7], v[108:111], v[32:47]
	v_mfma_f32_32x32x16_bf16 v[16:31], v[56:59], v[100:103], v[16:31]
	v_mfma_f32_32x32x16_bf16 v[32:47], v[12:15], v[104:107], v[32:47]
	v_mov_b64_e32 v[0:1], s[68:69]
	v_mov_b64_e32 v[14:15], s[82:83]
	v_mov_b64_e32 v[2:3], s[70:71]
	v_mov_b64_e32 v[4:5], s[72:73]
	v_mov_b64_e32 v[6:7], s[74:75]
	v_mov_b64_e32 v[8:9], s[76:77]
	v_mov_b64_e32 v[10:11], s[78:79]
	v_mfma_f32_32x32x16_bf16 v[16:31], v[64:67], v[96:99], v[16:31]
	v_mov_b64_e32 v[12:13], s[80:81]
	v_mfma_f32_32x32x16_bf16 v[32:47], v[52:55], v[100:103], v[32:47]
	s_nop 9
	v_max_f32_e32 v48, v17, v17
	v_max_f32_e32 v49, v16, v16
	v_max_f32_e32 v48, v49, v48
	v_max3_f32 v48, v48, v18, v19
	v_max3_f32 v48, v48, v20, v21
	v_max3_f32 v48, v48, v22, v23
	v_max3_f32 v48, v48, v24, v25
	v_mfma_f32_32x32x16_bf16 v[32:47], v[60:63], v[96:99], v[32:47]
	v_max3_f32 v48, v48, v26, v27
	v_max3_f32 v48, v48, v28, v29
	v_max3_f32 v48, v48, v30, v31
	s_nop 8
	v_max3_f32 v48, v48, v32, v33
	v_max3_f32 v48, v48, v34, v35
	v_max3_f32 v48, v48, v36, v37
	v_max3_f32 v48, v48, v38, v39
	v_max3_f32 v48, v48, v40, v41
	v_max3_f32 v48, v48, v42, v43
	v_max3_f32 v48, v48, v44, v45
	v_max3_f32 v48, v48, v46, v47
	v_mov_b32_e32 v49, v48
	s_nop 1
	v_permlane32_swap_b32_e32 v48, v49
	v_max_f32_e32 v49, v49, v49
	v_max_f32_e32 v48, v48, v48
	v_max_f32_e32 v48, v48, v49
	v_add_f32_e32 v49, 0x7149f2ca, v48
	v_cmp_ge_f32_e32 vcc, s37, v49
	s_cmp_eq_u64 vcc, exec
	v_max_f32_e32 v48, 0xf149f2ca, v48
	s_cselect_b64 vcc, -1, 0
	v_cndmask_b32_e32 v172, v48, v167, vcc
	v_sub_f32_e32 v49, 0xf149f2ca, v48
	v_mul_f32_e32 v48, 0xbdd53b94, v172
	v_fmamk_f32 v16, v16, 0x3dd53b94, v48
	v_exp_f32_e32 v186, v16
	v_fmamk_f32 v16, v17, 0x3dd53b94, v48
	v_exp_f32_e32 v189, v16
	v_fmamk_f32 v16, v18, 0x3dd53b94, v48
	v_exp_f32_e32 v187, v16
	v_fmamk_f32 v16, v19, 0x3dd53b94, v48
	v_exp_f32_e32 v190, v16
	v_fmamk_f32 v16, v20, 0x3dd53b94, v48
	v_exp_f32_e32 v188, v16
	v_fmamk_f32 v16, v21, 0x3dd53b94, v48
	v_exp_f32_e32 v191, v16
	v_fmamk_f32 v16, v22, 0x3dd53b94, v48
	v_exp_f32_e32 v184, v16
	v_fmamk_f32 v16, v23, 0x3dd53b94, v48
	v_exp_f32_e32 v185, v16
	v_fmamk_f32 v16, v24, 0x3dd53b94, v48
	v_mul_f32_e32 v49, 0x3dd53b94, v49
	v_exp_f32_e32 v180, v16
	v_fmamk_f32 v16, v25, 0x3dd53b94, v48
	v_exp_f32_e32 v49, v49
	v_exp_f32_e32 v182, v16
	v_fmamk_f32 v16, v26, 0x3dd53b94, v48
	v_exp_f32_e32 v181, v16
	v_fmamk_f32 v16, v27, 0x3dd53b94, v48
	v_exp_f32_e32 v183, v16
	v_fmamk_f32 v16, v28, 0x3dd53b94, v48
	v_exp_f32_e32 v176, v16
	v_fmamk_f32 v16, v29, 0x3dd53b94, v48
	s_add_i32 s4, s34, s1
	v_pk_fma_f32 v[144:145], v[46:47], s[6:7], v[48:49] op_sel_hi:[1,0,0]
	v_pk_fma_f32 v[156:157], v[44:45], s[6:7], v[48:49] op_sel_hi:[1,0,0]
	v_pk_fma_f32 v[160:161], v[42:43], s[6:7], v[48:49] op_sel_hi:[1,0,0]
	v_pk_fma_f32 v[146:147], v[40:41], s[6:7], v[48:49] op_sel_hi:[1,0,0]
	v_pk_fma_f32 v[154:155], v[38:39], s[6:7], v[48:49] op_sel_hi:[1,0,0]
	v_pk_fma_f32 v[158:159], v[36:37], s[6:7], v[48:49] op_sel_hi:[1,0,0]
	v_pk_fma_f32 v[162:163], v[34:35], s[6:7], v[48:49] op_sel_hi:[1,0,0]
	v_pk_fma_f32 v[164:165], v[32:33], s[6:7], v[48:49] op_sel_hi:[1,0,0]
	v_exp_f32_e32 v178, v16
	v_fmamk_f32 v16, v30, 0x3dd53b94, v48
	v_fmac_f32_e32 v48, 0x3dd53b94, v31
	s_mul_i32 s1, s4, 0x110000
	v_exp_f32_e32 v177, v16
	v_exp_f32_e32 v179, v48
	s_mul_hi_i32 s5, s4, 0x110000
	s_add_u32 s1, s86, s1
	s_addc_u32 s45, s87, s5
	s_mul_hi_i32 s5, s4, 0x198000
	s_mul_i32 s4, s4, 0x198000
	v_cndmask_b32_e64 v171, v49, 1.0, vcc
	s_add_u32 s46, s86, s4
	v_mov_b64_e32 v[62:63], v[14:15]
	v_mov_b64_e32 v[46:47], v[14:15]
	v_mov_b64_e32 v[30:31], v[14:15]
	s_addc_u32 s47, s87, s5
	s_add_i32 s48, s42, 0x4000
	v_mov_b64_e32 v[60:61], v[12:13]
	v_mov_b64_e32 v[58:59], v[10:11]
	v_mov_b64_e32 v[56:57], v[8:9]
	v_mov_b64_e32 v[54:55], v[6:7]
	v_mov_b64_e32 v[52:53], v[4:5]
	v_mov_b64_e32 v[50:51], v[2:3]
	v_mov_b64_e32 v[48:49], v[0:1]
	v_mov_b64_e32 v[44:45], v[12:13]
	v_mov_b64_e32 v[42:43], v[10:11]
	v_mov_b64_e32 v[40:41], v[8:9]
	v_mov_b64_e32 v[38:39], v[6:7]
	v_mov_b64_e32 v[36:37], v[4:5]
	v_mov_b64_e32 v[34:35], v[2:3]
	v_mov_b64_e32 v[32:33], v[0:1]
	v_mov_b64_e32 v[28:29], v[12:13]
	v_mov_b64_e32 v[26:27], v[10:11]
	v_mov_b64_e32 v[24:25], v[8:9]
	v_mov_b64_e32 v[22:23], v[6:7]
	v_mov_b64_e32 v[20:21], v[4:5]
	v_mov_b64_e32 v[18:19], v[2:3]
	v_mov_b64_e32 v[16:17], v[0:1]
	v_and_b32_e32 v65, 31, v166
	v_lshlrev_b32_e32 v66, 3, v166
	v_and_b32_e32 v66, 0x70, v66
	v_lshrrev_b32_e32 v64, 1, v166
	v_and_b32_e32 v64, 16, v64
	s_movk_i32 s98, 0x6000
	v_mov_b32_e32 v67, s98
	v_mad_u32_u24 v65, v65, s29, v67
	v_xad_u32 v208, v64, v66, v65
	v_or_b32_e32 v67, 32, v64
	v_xad_u32 v209, v67, v66, v65
	v_or_b32_e32 v67, 64, v64
	v_xad_u32 v210, v67, v66, v65
	v_or_b32_e32 v67, 0x60, v64
	v_xad_u32 v211, v67, v66, v65
	v_lshlrev_b32_e32 v64, 3, v166
	v_lshlrev_b32_e32 v65, 4, v166
	v_lshlrev_b32_e32 v66, 1, v166
	v_and_b32_e32 v67, 24, v64
	v_and_b32_e32 v65, 0xc0, v65
	v_and_b32_e32 v66, 32, v66
	v_or3_b32 v66, v67, v65, v66
	v_and_b32_e32 v64, 0x100, v64
	v_add_u32_e32 v212, v64, v66
.LBB0_450:
	s_add_u32 s34, s46, s22
	s_addc_u32 s35, s47, s23
	s_mov_b32 m0, s42
	s_add_u32 s98, s34, s24
	s_addc_u32 s99, s35, s25
	global_load_lds_dwordx4 v203, s[98:99]
	s_mov_b32 m0, s43
	s_add_i32 s4, s41, s50
	global_load_lds_dwordx4 v204, s[98:99]
	s_mov_b32 m0, s48
	s_nop 0
	global_load_lds_dwordx4 v205, s[98:99]
	s_add_u32 s58, s1, s22
	s_addc_u32 s59, s45, s23
	s_mov_b32 m0, s4
	s_mov_b32 s51, s49
	s_add_u32 s100, s58, s26
	s_addc_u32 s101, s59, s27
	global_load_lds_dwordx4 v206, s[100:101]
	s_add_i32 m0, s4, 0x2000
	s_mov_b32 s49, s68
	global_load_lds_dwordx4 v207, s[100:101]
	ds_read_b128 v[64:67], v208 offset:49152
	ds_read_b128 v[68:71], v208 offset:61440
	ds_read_b128 v[222:225], v209 offset:49152
	ds_read_b128 v[226:229], v209 offset:61440
	ds_read_b128 v[192:195], v210 offset:49152
	ds_read_b128 v[196:199], v210 offset:61440
	s_add_i32 s57, 0, 0x12000
	s_waitcnt lgkmcnt(4)
	v_mfma_f32_32x32x16_bf16 v[80:95], v[64:67], v[140:143], 0
	v_exp_f32_e32 v200, v144
	v_add_f32_e32 v144, 0, v186
	v_add_f32_e32 v144, v189, v144
	v_add_f32_e32 v144, v187, v144
	v_add_f32_e32 v144, v190, v144
	v_add_f32_e32 v144, v188, v144
	v_mfma_f32_32x32x16_bf16 v[64:79], v[68:71], v[140:143], 0
	ds_read_b128 v[214:217], v211 offset:49152
	ds_read_b128 v[218:221], v211 offset:61440
	v_add_f32_e32 v144, v191, v144
	v_add_f32_e32 v144, v184, v144
	v_add_f32_e32 v144, v185, v144
	v_add_f32_e32 v144, v180, v144
	v_add_f32_e32 v144, v182, v144
	v_add_f32_e32 v144, v181, v144
	v_add_f32_e32 v144, v183, v144
	s_waitcnt lgkmcnt(4)
	v_mfma_f32_32x32x16_bf16 v[80:95], v[222:225], v[136:139], v[80:95]
	v_add_f32_e32 v144, v176, v144
	v_add_f32_e32 v144, v178, v144
	v_exp_f32_e32 v162, v162
	v_add_f32_e32 v144, v177, v144
	v_exp_f32_e32 v163, v163
	v_add_f32_e32 v144, v179, v144
	v_exp_f32_e32 v201, v145
	v_mfma_f32_32x32x16_bf16 v[64:79], v[226:229], v[136:139], v[64:79]
	ds_read_b128 v[222:225], v208 offset:49280
	ds_read_b128 v[226:229], v208 offset:61568
	s_waitcnt lgkmcnt(4)
	v_mfma_f32_32x32x16_bf16 v[80:95], v[192:195], v[132:135], v[80:95]
	v_mfma_f32_32x32x16_bf16 v[64:79], v[196:199], v[132:135], v[64:79]
	ds_read_b128 v[192:195], v209 offset:49280
	ds_read_b128 v[196:199], v209 offset:61568
	s_waitcnt lgkmcnt(4)
	v_mfma_f32_32x32x16_bf16 v[80:95], v[214:217], v[128:131], v[80:95]
	v_mfma_f32_32x32x16_bf16 v[64:79], v[218:221], v[128:131], v[64:79]
	ds_read_b128 v[214:217], v210 offset:49280
	ds_read_b128 v[218:221], v210 offset:61568
	s_waitcnt lgkmcnt(4)
	v_mfma_f32_32x32x16_bf16 v[80:95], v[222:225], v[124:127], v[80:95]
	v_mfma_f32_32x32x16_bf16 v[64:79], v[226:229], v[124:127], v[64:79]
	ds_read_b128 v[222:225], v211 offset:49280
	ds_read_b128 v[226:229], v211 offset:61568
	s_waitcnt lgkmcnt(4)
	v_mfma_f32_32x32x16_bf16 v[80:95], v[192:195], v[120:123], v[80:95]
	v_mfma_f32_32x32x16_bf16 v[64:79], v[196:199], v[120:123], v[64:79]
	ds_read_b128 v[192:195], v208 offset:49408
	ds_read_b128 v[196:199], v208 offset:61696
	s_waitcnt lgkmcnt(4)
	v_mfma_f32_32x32x16_bf16 v[80:95], v[214:217], v[116:119], v[80:95]
	v_mfma_f32_32x32x16_bf16 v[64:79], v[218:221], v[116:119], v[64:79]
	ds_read_b128 v[214:217], v209 offset:49408
	ds_read_b128 v[218:221], v209 offset:61696
	s_waitcnt lgkmcnt(4)
	v_mfma_f32_32x32x16_bf16 v[80:95], v[222:225], v[112:115], v[80:95]
	v_mfma_f32_32x32x16_bf16 v[64:79], v[226:229], v[112:115], v[64:79]
	ds_read_b128 v[222:225], v210 offset:49408
	ds_read_b128 v[226:229], v210 offset:61696
	v_exp_f32_e32 v148, v164
	v_exp_f32_e32 v164, v165
	v_exp_f32_e32 v165, v158
	v_add_f32_e32 v144, v148, v144
	v_add_f32_e32 v144, v164, v144
	s_waitcnt lgkmcnt(4)
	v_mfma_f32_32x32x16_bf16 v[80:95], v[192:195], v[108:111], v[80:95]
	v_add_f32_e32 v144, v162, v144
	v_add_f32_e32 v144, v163, v144
	v_add_f32_e32 v144, v165, v144
	v_mfma_f32_32x32x16_bf16 v[64:79], v[196:199], v[108:111], v[64:79]
	ds_read_b128 v[192:195], v211 offset:49408
	ds_read_b128 v[196:199], v211 offset:61696
	s_waitcnt lgkmcnt(4)
	v_mfma_f32_32x32x16_bf16 v[80:95], v[214:217], v[104:107], v[80:95]
	v_mfma_f32_32x32x16_bf16 v[64:79], v[218:221], v[104:107], v[64:79]
	s_waitcnt lgkmcnt(2)
	v_mfma_f32_32x32x16_bf16 v[80:95], v[222:225], v[100:103], v[80:95]
	v_mfma_f32_32x32x16_bf16 v[64:79], v[226:229], v[100:103], v[64:79]
	v_exp_f32_e32 v175, v159
	s_nop 0
	v_add_f32_e32 v144, v175, v144
	s_waitcnt lgkmcnt(0)
	v_mfma_f32_32x32x16_bf16 v[80:95], v[192:195], v[96:99], v[80:95]
	v_exp_f32_e32 v192, v154
	v_exp_f32_e32 v193, v155
	v_exp_f32_e32 v194, v146
	v_exp_f32_e32 v195, v147
	v_add_f32_e32 v144, v192, v144
	v_add_f32_e32 v144, v193, v144
	v_add_f32_e32 v144, v194, v144
	v_mfma_f32_32x32x16_bf16 v[64:79], v[196:199], v[96:99], v[64:79]
	v_exp_f32_e32 v196, v160
	v_exp_f32_e32 v197, v161
	v_exp_f32_e32 v198, v156
	v_exp_f32_e32 v199, v157
	v_add_f32_e32 v144, v195, v144
	v_add_f32_e32 v144, v196, v144
	v_add_f32_e32 v144, v197, v144
	v_add_f32_e32 v144, v198, v144
	v_add_f32_e32 v144, v199, v144
	v_add_f32_e32 v144, v200, v144
	v_add_f32_e32 v173, v201, v144
	v_mov_b32_e32 v174, v173
	v_cvt_pk_bf16_f32 v144, v186, v189
	v_cvt_pk_bf16_f32 v145, v187, v190
	v_cvt_pk_bf16_f32 v146, v188, v191
	s_nop 1
	v_permlane32_swap_b32_e32 v173, v174
	v_cvt_pk_bf16_f32 v147, v184, v185
	v_permlane32_swap_b32_e32 v144, v146
	v_cvt_pk_bf16_f32 v154, v180, v182
	v_cvt_pk_bf16_f32 v155, v181, v183
	v_cvt_pk_bf16_f32 v156, v176, v178
	v_cvt_pk_bf16_f32 v157, v177, v179
	v_cvt_pk_bf16_f32 v158, v148, v164
	v_cvt_pk_bf16_f32 v159, v162, v163
	v_cvt_pk_bf16_f32 v160, v165, v175
	v_cvt_pk_bf16_f32 v161, v192, v193
	v_cvt_pk_bf16_f32 v162, v194, v195
	v_cvt_pk_bf16_f32 v163, v196, v197
	v_cvt_pk_bf16_f32 v164, v198, v199
	v_cvt_pk_bf16_f32 v165, v200, v201
	v_permlane32_swap_b32_e32 v145, v147
	v_permlane32_swap_b32_e32 v154, v156
	v_permlane32_swap_b32_e32 v155, v157
	v_permlane32_swap_b32_e32 v158, v160
	v_permlane32_swap_b32_e32 v159, v161
	v_permlane32_swap_b32_e32 v162, v164
	v_permlane32_swap_b32_e32 v163, v165
	s_cmp_lg_u32 0, -1
	s_cselect_b32 s4, 0, 0
	s_add_i32 s44, s68, s4
	v_add_u32_e32 v148, s44, v212
	ds_read_b64_tr_b16 v[176:177], v148 offset:0
	ds_read_b64_tr_b16 v[178:179], v148 offset:0x800
	ds_read_b64_tr_b16 v[180:181], v148 offset:0x1000
	ds_read_b64_tr_b16 v[182:183], v148 offset:0x1800
	ds_read_b64_tr_b16 v[184:185], v148 offset:0x2000
	ds_read_b64_tr_b16 v[186:187], v148 offset:0x2800
	ds_read_b64_tr_b16 v[188:189], v148 offset:0x3000
	ds_read_b64_tr_b16 v[190:191], v148 offset:0x3800
	s_waitcnt lgkmcnt(0)
	s_nop 0
	v_mfma_f32_32x32x16_bf16 v[0:15], v[144:147], v[176:179], v[0:15]
	ds_read_b64_tr_b16 v[176:177], v148 offset:0x200
	ds_read_b64_tr_b16 v[178:179], v148 offset:0xa00
	v_mfma_f32_32x32x16_bf16 v[0:15], v[154:157], v[180:183], v[0:15]
	ds_read_b64_tr_b16 v[180:181], v148 offset:0x1200
	ds_read_b64_tr_b16 v[182:183], v148 offset:0x1a00
	v_mfma_f32_32x32x16_bf16 v[0:15], v[158:161], v[184:187], v[0:15]
	ds_read_b64_tr_b16 v[184:185], v148 offset:0x2200
	ds_read_b64_tr_b16 v[186:187], v148 offset:0x2a00
	v_mfma_f32_32x32x16_bf16 v[0:15], v[162:165], v[188:191], v[0:15]
	ds_read_b64_tr_b16 v[188:189], v148 offset:0x3200
	ds_read_b64_tr_b16 v[190:191], v148 offset:0x3a00
	s_waitcnt lgkmcnt(0)
	v_mfma_f32_32x32x16_bf16 v[48:63], v[144:147], v[176:179], v[48:63]
	ds_read_b64_tr_b16 v[176:177], v148 offset:0x400
	ds_read_b64_tr_b16 v[178:179], v148 offset:0xc00
	v_mfma_f32_32x32x16_bf16 v[48:63], v[154:157], v[180:183], v[48:63]
	ds_read_b64_tr_b16 v[180:181], v148 offset:0x1400
	ds_read_b64_tr_b16 v[182:183], v148 offset:0x1c00
	v_mfma_f32_32x32x16_bf16 v[48:63], v[158:161], v[184:187], v[48:63]
	ds_read_b64_tr_b16 v[184:185], v148 offset:0x2400
	ds_read_b64_tr_b16 v[186:187], v148 offset:0x2c00
	v_mfma_f32_32x32x16_bf16 v[48:63], v[162:165], v[188:191], v[48:63]
	ds_read_b64_tr_b16 v[188:189], v148 offset:0x3400
	ds_read_b64_tr_b16 v[190:191], v148 offset:0x3c00
	s_waitcnt lgkmcnt(0)
	v_mfma_f32_32x32x16_bf16 v[32:47], v[144:147], v[176:179], v[32:47]
	ds_read_b64_tr_b16 v[176:177], v148 offset:0x600
	ds_read_b64_tr_b16 v[178:179], v148 offset:0xe00
	v_mfma_f32_32x32x16_bf16 v[32:47], v[154:157], v[180:183], v[32:47]
	ds_read_b64_tr_b16 v[180:181], v148 offset:0x1600
	ds_read_b64_tr_b16 v[182:183], v148 offset:0x1e00
	v_mfma_f32_32x32x16_bf16 v[32:47], v[158:161], v[184:187], v[32:47]
	ds_read_b64_tr_b16 v[184:185], v148 offset:0x2600
	ds_read_b64_tr_b16 v[186:187], v148 offset:0x2e00
	v_mfma_f32_32x32x16_bf16 v[32:47], v[162:165], v[188:191], v[32:47]
	ds_read_b64_tr_b16 v[188:189], v148 offset:0x3600
	ds_read_b64_tr_b16 v[190:191], v148 offset:0x3e00
	s_waitcnt lgkmcnt(0)
	v_mfma_f32_32x32x16_bf16 v[16:31], v[144:147], v[176:179], v[16:31]
	v_max_f32_e32 v144, v81, v81
	v_max_f32_e32 v145, v80, v80
	v_max_f32_e32 v144, v145, v144
	v_max3_f32 v144, v144, v82, v83
	v_max3_f32 v144, v144, v84, v85
	v_max3_f32 v144, v144, v86, v87
	v_max3_f32 v144, v144, v88, v89
	v_max3_f32 v144, v144, v90, v91
	v_max3_f32 v144, v144, v92, v93
	v_mfma_f32_32x32x16_bf16 v[16:31], v[154:157], v[180:183], v[16:31]
	v_max3_f32 v144, v144, v94, v95
	v_max3_f32 v144, v144, v64, v65
	v_max3_f32 v144, v144, v66, v67
	v_max3_f32 v144, v144, v68, v69
	v_max3_f32 v144, v144, v70, v71
	v_max3_f32 v144, v144, v72, v73
	v_max3_f32 v144, v144, v74, v75
	v_max3_f32 v144, v144, v76, v77
	v_mfma_f32_32x32x16_bf16 v[16:31], v[158:161], v[184:187], v[16:31]
	v_max3_f32 v144, v144, v78, v79
	v_mov_b32_e32 v145, v144
	s_nop 1
	v_permlane32_swap_b32_e32 v144, v145
	v_max_f32_e32 v145, v145, v145
	v_max_f32_e32 v144, v144, v144
	v_max_f32_e32 v144, v144, v145
	v_sub_f32_e32 v145, v144, v172
	v_cmp_ge_f32_e32 vcc, s37, v145
	v_max_f32_e32 v145, v172, v172
	v_max_f32_e32 v144, v145, v144
	v_mfma_f32_32x32x16_bf16 v[16:31], v[162:165], v[188:191], v[16:31]
	v_sub_f32_e32 v145, v172, v144
	v_mul_f32_e32 v145, 0x3dd53b94, v145
	v_exp_f32_e32 v145, v145
	s_cmp_eq_u64 vcc, exec
	s_cselect_b64 s[4:5], -1, 0
	s_waitcnt vmcnt(0)
	v_cndmask_b32_e64 v175, v145, 1.0, s[4:5]
	v_cmp_gt_f32_e32 vcc, 1.0, v175
	s_waitcnt vmcnt(0)
	s_barrier
	s_cbranch_vccz .LBB0_454
	s_and_saveexec_b64 s[60:61], s[2:3]
	ds_write_b32 v153, v175 offset:128
	s_or_b64 exec, exec, s[60:61]
	s_waitcnt lgkmcnt(0)
	v_add_u32_e32 v145, v151, v152
	ds_read_b128 v[154:157], v145 offset:224
	ds_read_b128 v[158:161], v145 offset:192
	ds_read_b128 v[162:165], v145 offset:160
	ds_read_b128 v[176:179], v145 offset:128
	s_waitcnt lgkmcnt(3)
	v_pk_mul_f32 v[12:13], v[12:13], v[154:155]
	s_waitcnt lgkmcnt(2)
	v_pk_mul_f32 v[8:9], v[8:9], v[158:159]
	s_waitcnt lgkmcnt(1)
	v_pk_mul_f32 v[4:5], v[4:5], v[162:163]
	v_pk_mul_f32 v[14:15], v[14:15], v[156:157]
	v_pk_mul_f32 v[10:11], v[10:11], v[160:161]
	v_pk_mul_f32 v[6:7], v[6:7], v[164:165]
	s_waitcnt lgkmcnt(0)
	v_pk_mul_f32 v[2:3], v[2:3], v[178:179]
	v_pk_mul_f32 v[0:1], v[0:1], v[176:177]
	v_pk_mul_f32 v[60:61], v[60:61], v[154:155]
	v_pk_mul_f32 v[56:57], v[56:57], v[158:159]
	v_pk_mul_f32 v[52:53], v[52:53], v[162:163]
	v_pk_mul_f32 v[62:63], v[62:63], v[156:157]
	v_pk_mul_f32 v[58:59], v[58:59], v[160:161]
	v_pk_mul_f32 v[54:55], v[54:55], v[164:165]
	v_pk_mul_f32 v[50:51], v[50:51], v[178:179]
	v_pk_mul_f32 v[48:49], v[48:49], v[176:177]
	v_pk_mul_f32 v[44:45], v[44:45], v[154:155]
	v_pk_mul_f32 v[40:41], v[40:41], v[158:159]
	v_pk_mul_f32 v[36:37], v[36:37], v[162:163]
	v_pk_mul_f32 v[46:47], v[46:47], v[156:157]
	v_pk_mul_f32 v[42:43], v[42:43], v[160:161]
	v_pk_mul_f32 v[38:39], v[38:39], v[164:165]
	v_pk_mul_f32 v[34:35], v[34:35], v[178:179]
	v_pk_mul_f32 v[32:33], v[32:33], v[176:177]
	v_pk_mul_f32 v[28:29], v[28:29], v[154:155]
	v_pk_mul_f32 v[24:25], v[24:25], v[158:159]
	v_pk_mul_f32 v[20:21], v[20:21], v[162:163]
	v_pk_mul_f32 v[30:31], v[30:31], v[156:157]
	v_pk_mul_f32 v[26:27], v[26:27], v[160:161]
	v_pk_mul_f32 v[22:23], v[22:23], v[164:165]
	v_pk_mul_f32 v[18:19], v[18:19], v[178:179]
	v_pk_mul_f32 v[16:17], v[16:17], v[176:177]
.LBB0_454:
	v_cndmask_b32_e64 v154, v144, v172, s[4:5]
	v_mul_f32_e32 v176, 0xbdd53b94, v154
	v_fmamk_f32 v187, v66, 0x3dd53b94, v176
	v_fmamk_f32 v185, v64, 0x3dd53b94, v176
	v_fmamk_f32 v186, v65, 0x3dd53b94, v176
	v_fmamk_f32 v188, v67, 0x3dd53b94, v176
	s_cmp_lg_u32 0, -1
	s_cselect_b32 s4, 0, 0
	s_add_i32 s5, s4, s40
	s_add_i32 m0, s5, 0x12000
	v_fmamk_f32 v178, v69, 0x3dd53b94, v176
	s_add_u32 s98, s34, s52
	s_addc_u32 s99, s35, s53
	global_load_lds_dwordx4 v203, s[98:99]
	s_add_i32 m0, s5, 0x14000
	v_fmamk_f32 v179, v70, 0x3dd53b94, v176
	global_load_lds_dwordx4 v204, s[98:99]
	s_add_i32 m0, s5, 0x16000
	v_fmamk_f32 v189, v68, 0x3dd53b94, v176
	global_load_lds_dwordx4 v205, s[98:99]
	v_fmamk_f32 v180, v71, 0x3dd53b94, v176
	s_add_i32 s5, s41, s49
	s_mov_b32 m0, s5
	v_fmamk_f32 v80, v80, 0x3dd53b94, v176
	s_add_u32 s100, s58, s54
	s_addc_u32 s101, s59, s55
	global_load_lds_dwordx4 v206, s[100:101]
	s_add_i32 m0, s5, 0x2000
	v_exp_f32_e32 v144, v80
	global_load_lds_dwordx4 v207, s[100:101]
	v_fmamk_f32 v81, v81, 0x3dd53b94, v176
	v_fmamk_f32 v82, v82, 0x3dd53b94, v176
	v_fmamk_f32 v83, v83, 0x3dd53b94, v176
	v_fmamk_f32 v84, v84, 0x3dd53b94, v176
	v_fmamk_f32 v85, v85, 0x3dd53b94, v176
	v_fmamk_f32 v86, v86, 0x3dd53b94, v176
	v_fmamk_f32 v87, v87, 0x3dd53b94, v176
	v_fmamk_f32 v88, v88, 0x3dd53b94, v176
	v_fmamk_f32 v89, v89, 0x3dd53b94, v176
	v_fmamk_f32 v90, v90, 0x3dd53b94, v176
	v_fmamk_f32 v91, v91, 0x3dd53b94, v176
	v_fmamk_f32 v92, v92, 0x3dd53b94, v176
	v_fmamk_f32 v93, v93, 0x3dd53b94, v176
	v_fmamk_f32 v94, v94, 0x3dd53b94, v176
	v_fmamk_f32 v95, v95, 0x3dd53b94, v176
	v_fmamk_f32 v181, v72, 0x3dd53b94, v176
	v_fmamk_f32 v182, v73, 0x3dd53b94, v176
	v_fmamk_f32 v183, v74, 0x3dd53b94, v176
	v_fmamk_f32 v184, v75, 0x3dd53b94, v176
	v_fmamk_f32 v177, v76, 0x3dd53b94, v176
	v_exp_f32_e32 v172, v81
	v_exp_f32_e32 v145, v82
	v_exp_f32_e32 v165, v83
	v_exp_f32_e32 v146, v84
	v_exp_f32_e32 v164, v85
	v_exp_f32_e32 v147, v86
	v_exp_f32_e32 v163, v87
	v_exp_f32_e32 v160, v88
	v_exp_f32_e32 v162, v89
	v_exp_f32_e32 v159, v90
	v_exp_f32_e32 v161, v91
	v_exp_f32_e32 v156, v92
	v_exp_f32_e32 v158, v93
	v_exp_f32_e32 v155, v94
	v_exp_f32_e32 v157, v95
	v_fmamk_f32 v190, v77, 0x3dd53b94, v176
	v_fmamk_f32 v191, v78, 0x3dd53b94, v176
	v_fmac_f32_e32 v176, 0x3dd53b94, v79
	ds_read_b128 v[64:67], v208 offset:24576
	ds_read_b128 v[68:71], v208 offset:36864
	ds_read_b128 v[222:225], v209 offset:24576
	ds_read_b128 v[226:229], v209 offset:36864
	ds_read_b128 v[192:195], v210 offset:24576
	ds_read_b128 v[196:199], v210 offset:36864
	v_exp_f32_e32 v178, v178
	s_waitcnt lgkmcnt(4)
	v_mfma_f32_32x32x16_bf16 v[80:95], v[64:67], v[140:143], 0
	v_exp_f32_e32 v179, v179
	v_exp_f32_e32 v180, v180
	v_exp_f32_e32 v181, v181
	v_exp_f32_e32 v182, v182
	v_exp_f32_e32 v183, v183
	v_exp_f32_e32 v184, v184
	v_mfma_f32_32x32x16_bf16 v[64:79], v[68:71], v[140:143], 0
	ds_read_b128 v[214:217], v211 offset:24576
	ds_read_b128 v[218:221], v211 offset:36864
	v_exp_f32_e32 v190, v190
	v_exp_f32_e32 v191, v191
	s_waitcnt lgkmcnt(4)
	v_mfma_f32_32x32x16_bf16 v[80:95], v[222:225], v[136:139], v[80:95]
	v_mfma_f32_32x32x16_bf16 v[64:79], v[226:229], v[136:139], v[64:79]
	ds_read_b128 v[222:225], v208 offset:24704
	ds_read_b128 v[226:229], v208 offset:36992
	s_waitcnt lgkmcnt(4)
	v_mfma_f32_32x32x16_bf16 v[80:95], v[192:195], v[132:135], v[80:95]
	v_mfma_f32_32x32x16_bf16 v[64:79], v[196:199], v[132:135], v[64:79]
	ds_read_b128 v[192:195], v209 offset:24704
	ds_read_b128 v[196:199], v209 offset:36992
	s_waitcnt lgkmcnt(4)
	v_mfma_f32_32x32x16_bf16 v[80:95], v[214:217], v[128:131], v[80:95]
	v_mfma_f32_32x32x16_bf16 v[64:79], v[218:221], v[128:131], v[64:79]
	ds_read_b128 v[214:217], v210 offset:24704
	ds_read_b128 v[218:221], v210 offset:36992
	s_waitcnt lgkmcnt(4)
	v_mfma_f32_32x32x16_bf16 v[80:95], v[222:225], v[124:127], v[80:95]
	v_mfma_f32_32x32x16_bf16 v[64:79], v[226:229], v[124:127], v[64:79]
	ds_read_b128 v[222:225], v211 offset:24704
	ds_read_b128 v[226:229], v211 offset:36992
	s_waitcnt lgkmcnt(4)
	v_mfma_f32_32x32x16_bf16 v[80:95], v[192:195], v[120:123], v[80:95]
	v_mfma_f32_32x32x16_bf16 v[64:79], v[196:199], v[120:123], v[64:79]
	ds_read_b128 v[192:195], v208 offset:24832
	ds_read_b128 v[196:199], v208 offset:37120
	s_waitcnt lgkmcnt(4)
	v_mfma_f32_32x32x16_bf16 v[80:95], v[214:217], v[116:119], v[80:95]
	v_mfma_f32_32x32x16_bf16 v[64:79], v[218:221], v[116:119], v[64:79]
	ds_read_b128 v[214:217], v209 offset:24832
	ds_read_b128 v[218:221], v209 offset:37120
	s_waitcnt lgkmcnt(4)
	v_mfma_f32_32x32x16_bf16 v[80:95], v[222:225], v[112:115], v[80:95]
	v_mfma_f32_32x32x16_bf16 v[64:79], v[226:229], v[112:115], v[64:79]
	ds_read_b128 v[222:225], v210 offset:24832
	ds_read_b128 v[226:229], v210 offset:37120
	v_exp_f32_e32 v148, v185
	v_exp_f32_e32 v185, v186
	v_exp_f32_e32 v186, v187
	v_exp_f32_e32 v187, v188
	v_exp_f32_e32 v188, v189
	v_exp_f32_e32 v189, v177
	s_waitcnt lgkmcnt(4)
	v_mfma_f32_32x32x16_bf16 v[80:95], v[192:195], v[108:111], v[80:95]
	v_mfma_f32_32x32x16_bf16 v[64:79], v[196:199], v[108:111], v[64:79]
	ds_read_b128 v[192:195], v211 offset:24832
	ds_read_b128 v[196:199], v211 offset:37120
	s_waitcnt lgkmcnt(4)
	v_mfma_f32_32x32x16_bf16 v[80:95], v[214:217], v[104:107], v[80:95]
	v_mfma_f32_32x32x16_bf16 v[64:79], v[218:221], v[104:107], v[64:79]
	s_waitcnt lgkmcnt(2)
	v_mfma_f32_32x32x16_bf16 v[80:95], v[222:225], v[100:103], v[80:95]
	v_mfma_f32_32x32x16_bf16 v[64:79], v[226:229], v[100:103], v[64:79]
	s_waitcnt lgkmcnt(0)
	v_mfma_f32_32x32x16_bf16 v[80:95], v[192:195], v[96:99], v[80:95]
	v_exp_f32_e32 v194, v176
	v_add_f32_e32 v176, 0, v144
	v_add_f32_e32 v176, v172, v176
	v_add_f32_e32 v176, v145, v176
	v_add_f32_e32 v176, v165, v176
	v_add_f32_e32 v176, v146, v176
	v_add_f32_e32 v176, v164, v176
	v_add_f32_e32 v176, v147, v176
	v_add_f32_e32 v176, v163, v176
	v_add_f32_e32 v176, v160, v176
	v_add_f32_e32 v176, v162, v176
	v_add_f32_e32 v176, v159, v176
	v_add_f32_e32 v176, v161, v176
	v_add_f32_e32 v176, v156, v176
	v_add_f32_e32 v176, v158, v176
	v_add_f32_e32 v176, v155, v176
	v_add_f32_e32 v176, v157, v176
	v_add_f32_e32 v176, v148, v176
	v_add_f32_e32 v176, v185, v176
	v_add_f32_e32 v176, v186, v176
	v_add_f32_e32 v176, v187, v176
	v_add_f32_e32 v176, v188, v176
	v_add_f32_e32 v176, v178, v176
	v_add_f32_e32 v176, v179, v176
	v_add_f32_e32 v176, v180, v176
	v_add_f32_e32 v176, v181, v176
	v_add_f32_e32 v176, v182, v176
	v_mfma_f32_32x32x16_bf16 v[64:79], v[196:199], v[96:99], v[64:79]
	v_add_f32_e32 v176, v183, v176
	v_add_f32_e32 v176, v184, v176
	v_add_f32_e32 v176, v189, v176
	v_add_f32_e32 v176, v190, v176
	v_add_f32_e32 v176, v191, v176
	v_add_f32_e32 v192, v194, v176
	v_mov_b32_e32 v193, v192
	v_cvt_pk_bf16_f32 v144, v144, v172
	v_cvt_pk_bf16_f32 v145, v145, v165
	v_cvt_pk_bf16_f32 v146, v146, v164
	s_nop 1
	v_permlane32_swap_b32_e32 v192, v193
	v_cvt_pk_bf16_f32 v147, v147, v163
	v_permlane32_swap_b32_e32 v144, v146
	v_cvt_pk_bf16_f32 v160, v160, v162
	v_cvt_pk_bf16_f32 v161, v159, v161
	v_cvt_pk_bf16_f32 v162, v156, v158
	v_cvt_pk_bf16_f32 v163, v155, v157
	v_cvt_pk_bf16_f32 v156, v148, v185
	v_cvt_pk_bf16_f32 v157, v186, v187
	v_cvt_pk_bf16_f32 v158, v188, v178
	v_cvt_pk_bf16_f32 v159, v179, v180
	v_cvt_pk_bf16_f32 v176, v181, v182
	v_cvt_pk_bf16_f32 v177, v183, v184
	v_cvt_pk_bf16_f32 v178, v189, v190
	v_cvt_pk_bf16_f32 v179, v191, v194
	v_permlane32_swap_b32_e32 v145, v147
	v_permlane32_swap_b32_e32 v160, v162
	v_permlane32_swap_b32_e32 v161, v163
	v_permlane32_swap_b32_e32 v156, v158
	v_permlane32_swap_b32_e32 v157, v159
	v_permlane32_swap_b32_e32 v176, v178
	v_permlane32_swap_b32_e32 v177, v179
	s_add_i32 s4, s51, s4
	v_add_u32_e32 v148, s4, v212
	ds_read_b64_tr_b16 v[180:181], v148 offset:0
	ds_read_b64_tr_b16 v[182:183], v148 offset:0x800
	ds_read_b64_tr_b16 v[184:185], v148 offset:0x1000
	ds_read_b64_tr_b16 v[186:187], v148 offset:0x1800
	ds_read_b64_tr_b16 v[188:189], v148 offset:0x2000
	ds_read_b64_tr_b16 v[190:191], v148 offset:0x2800
	ds_read_b64_tr_b16 v[194:195], v148 offset:0x3000
	ds_read_b64_tr_b16 v[196:197], v148 offset:0x3800
	s_waitcnt lgkmcnt(0)
	s_nop 0
	v_mfma_f32_32x32x16_bf16 v[0:15], v[144:147], v[180:183], v[0:15]
	ds_read_b64_tr_b16 v[180:181], v148 offset:0x200
	ds_read_b64_tr_b16 v[182:183], v148 offset:0xa00
	v_mfma_f32_32x32x16_bf16 v[0:15], v[160:163], v[184:187], v[0:15]
	ds_read_b64_tr_b16 v[184:185], v148 offset:0x1200
	ds_read_b64_tr_b16 v[186:187], v148 offset:0x1a00
	v_mfma_f32_32x32x16_bf16 v[0:15], v[156:159], v[188:191], v[0:15]
	ds_read_b64_tr_b16 v[188:189], v148 offset:0x2200
	ds_read_b64_tr_b16 v[190:191], v148 offset:0x2a00
	v_mfma_f32_32x32x16_bf16 v[0:15], v[176:179], v[194:197], v[0:15]
	ds_read_b64_tr_b16 v[194:195], v148 offset:0x3200
	ds_read_b64_tr_b16 v[196:197], v148 offset:0x3a00
	s_waitcnt lgkmcnt(0)
	v_mfma_f32_32x32x16_bf16 v[48:63], v[144:147], v[180:183], v[48:63]
	ds_read_b64_tr_b16 v[180:181], v148 offset:0x400
	ds_read_b64_tr_b16 v[182:183], v148 offset:0xc00
	v_mfma_f32_32x32x16_bf16 v[48:63], v[160:163], v[184:187], v[48:63]
	ds_read_b64_tr_b16 v[184:185], v148 offset:0x1400
	ds_read_b64_tr_b16 v[186:187], v148 offset:0x1c00
	v_mfma_f32_32x32x16_bf16 v[48:63], v[156:159], v[188:191], v[48:63]
	ds_read_b64_tr_b16 v[188:189], v148 offset:0x2400
	ds_read_b64_tr_b16 v[190:191], v148 offset:0x2c00
	v_mfma_f32_32x32x16_bf16 v[48:63], v[176:179], v[194:197], v[48:63]
	ds_read_b64_tr_b16 v[194:195], v148 offset:0x3400
	ds_read_b64_tr_b16 v[196:197], v148 offset:0x3c00
	s_waitcnt lgkmcnt(0)
	v_mfma_f32_32x32x16_bf16 v[32:47], v[144:147], v[180:183], v[32:47]
	ds_read_b64_tr_b16 v[180:181], v148 offset:0x600
	ds_read_b64_tr_b16 v[182:183], v148 offset:0xe00
	v_mfma_f32_32x32x16_bf16 v[32:47], v[160:163], v[184:187], v[32:47]
	ds_read_b64_tr_b16 v[184:185], v148 offset:0x1600
	ds_read_b64_tr_b16 v[186:187], v148 offset:0x1e00
	v_mfma_f32_32x32x16_bf16 v[32:47], v[156:159], v[188:191], v[32:47]
	ds_read_b64_tr_b16 v[188:189], v148 offset:0x2600
	ds_read_b64_tr_b16 v[190:191], v148 offset:0x2e00
	v_mfma_f32_32x32x16_bf16 v[32:47], v[176:179], v[194:197], v[32:47]
	ds_read_b64_tr_b16 v[194:195], v148 offset:0x3600
	ds_read_b64_tr_b16 v[196:197], v148 offset:0x3e00
	s_waitcnt lgkmcnt(0)
	v_mfma_f32_32x32x16_bf16 v[16:31], v[144:147], v[180:183], v[16:31]
	v_max_f32_e32 v144, v81, v81
	v_max_f32_e32 v145, v80, v80
	v_max_f32_e32 v144, v145, v144
	v_max3_f32 v144, v144, v82, v83
	v_max3_f32 v144, v144, v84, v85
	v_max3_f32 v144, v144, v86, v87
	v_max3_f32 v144, v144, v88, v89
	v_max3_f32 v144, v144, v90, v91
	v_max3_f32 v144, v144, v92, v93
	v_mfma_f32_32x32x16_bf16 v[16:31], v[160:163], v[184:187], v[16:31]
	v_max3_f32 v144, v144, v94, v95
	v_max3_f32 v144, v144, v64, v65
	v_max3_f32 v144, v144, v66, v67
	v_max3_f32 v144, v144, v68, v69
	v_max3_f32 v144, v144, v70, v71
	v_max3_f32 v144, v144, v72, v73
	v_max3_f32 v144, v144, v74, v75
	v_max3_f32 v144, v144, v76, v77
	v_mfma_f32_32x32x16_bf16 v[16:31], v[156:159], v[188:191], v[16:31]
	v_max3_f32 v144, v144, v78, v79
	v_mov_b32_e32 v145, v144
	s_nop 1
	v_permlane32_swap_b32_e32 v144, v145
	v_max_f32_e32 v145, v145, v145
	v_max_f32_e32 v144, v144, v144
	v_max_f32_e32 v144, v144, v145
	v_sub_f32_e32 v145, v144, v154
	v_cmp_ge_f32_e32 vcc, s37, v145
	v_max_f32_e32 v145, v154, v154
	v_max_f32_e32 v144, v145, v144
	v_mfma_f32_32x32x16_bf16 v[16:31], v[176:179], v[194:197], v[16:31]
	v_sub_f32_e32 v145, v154, v144
	v_mul_f32_e32 v145, 0x3dd53b94, v145
	v_exp_f32_e32 v145, v145
	s_cmp_eq_u64 vcc, exec
	s_cselect_b64 s[4:5], -1, 0
	s_waitcnt vmcnt(0)
	v_cndmask_b32_e64 v148, v145, 1.0, s[4:5]
	v_cmp_gt_f32_e32 vcc, 1.0, v148
	s_waitcnt vmcnt(0)
	s_barrier
	s_cbranch_vccz .LBB0_458
	s_and_saveexec_b64 s[34:35], s[2:3]
	ds_write_b32 v153, v148 offset:128
	s_or_b64 exec, exec, s[34:35]
	s_waitcnt lgkmcnt(0)
	v_add_u32_e32 v145, v151, v152
	ds_read_b128 v[156:159], v145 offset:224
	ds_read_b128 v[160:163], v145 offset:192
	ds_read_b128 v[176:179], v145 offset:160
	ds_read_b128 v[180:183], v145 offset:128
	s_waitcnt lgkmcnt(3)
	v_pk_mul_f32 v[12:13], v[12:13], v[156:157]
	s_waitcnt lgkmcnt(2)
	v_pk_mul_f32 v[8:9], v[8:9], v[160:161]
	s_waitcnt lgkmcnt(1)
	v_pk_mul_f32 v[4:5], v[4:5], v[176:177]
	v_pk_mul_f32 v[14:15], v[14:15], v[158:159]
	v_pk_mul_f32 v[10:11], v[10:11], v[162:163]
	v_pk_mul_f32 v[6:7], v[6:7], v[178:179]
	s_waitcnt lgkmcnt(0)
	v_pk_mul_f32 v[2:3], v[2:3], v[182:183]
	v_pk_mul_f32 v[0:1], v[0:1], v[180:181]
	v_pk_mul_f32 v[60:61], v[60:61], v[156:157]
	v_pk_mul_f32 v[56:57], v[56:57], v[160:161]
	v_pk_mul_f32 v[52:53], v[52:53], v[176:177]
	v_pk_mul_f32 v[62:63], v[62:63], v[158:159]
	v_pk_mul_f32 v[58:59], v[58:59], v[162:163]
	v_pk_mul_f32 v[54:55], v[54:55], v[178:179]
	v_pk_mul_f32 v[50:51], v[50:51], v[182:183]
	v_pk_mul_f32 v[48:49], v[48:49], v[180:181]
	v_pk_mul_f32 v[44:45], v[44:45], v[156:157]
	v_pk_mul_f32 v[40:41], v[40:41], v[160:161]
	v_pk_mul_f32 v[36:37], v[36:37], v[176:177]
	v_pk_mul_f32 v[46:47], v[46:47], v[158:159]
	v_pk_mul_f32 v[42:43], v[42:43], v[162:163]
	v_pk_mul_f32 v[38:39], v[38:39], v[178:179]
	v_pk_mul_f32 v[34:35], v[34:35], v[182:183]
	v_pk_mul_f32 v[32:33], v[32:33], v[180:181]
	v_pk_mul_f32 v[28:29], v[28:29], v[156:157]
	v_pk_mul_f32 v[24:25], v[24:25], v[160:161]
	v_pk_mul_f32 v[20:21], v[20:21], v[176:177]
	v_pk_mul_f32 v[30:31], v[30:31], v[158:159]
	v_pk_mul_f32 v[26:27], v[26:27], v[162:163]
	v_pk_mul_f32 v[22:23], v[22:23], v[178:179]
	v_pk_mul_f32 v[18:19], v[18:19], v[182:183]
	v_pk_mul_f32 v[16:17], v[16:17], v[180:181]

.LBB0_1097:
	s_lshl_b32 s0, s75, 1
	s_and_b32 s0, s0, 14
	s_ashr_i32 s35, s75, 7
	s_add_i32 s28, s0, s35
	s_ashr_i32 s29, s28, 31
	s_lshl_b32 s2, s75, 5
	s_lshl_b64 s[0:1], s[28:29], 12
	s_and_b32 s29, s2, 0xf00
	s_or_b32 s0, s0, s29
	s_mulk_i32 s1, 0x180
	s_mul_hi_u32 s2, s0, 0x180
	s_and_b32 s34, s52, 14
	s_add_i32 s2, s2, s1
	s_mulk_i32 s0, 0x180
	v_mov_b32_e32 v68, v166
	s_add_u32 s0, s14, s0
	s_addc_u32 s1, s15, s2
	v_ashrrev_i32_e32 v2, 6, v68
	v_and_b32_e32 v168, 31, v68
	v_lshlrev_b32_e32 v146, 5, v2
	s_mul_i32 s3, s28, 0x198000
	v_bfe_u32 v169, v68, 5, 1
	v_or_b32_e32 v3, v146, v168
	v_mov_b64_e32 v[0:1], s[0:1]
	s_mul_hi_i32 s2, s28, 0x198000
	s_add_u32 s4, s19, s3
	v_mad_i64_i32 v[0:1], s[0:1], v3, s54, v[0:1]
	v_lshlrev_b32_e32 v148, 4, v169
	v_mov_b32_e32 v149, v145
	s_addc_u32 s5, s30, s2
	s_mul_i32 s2, s28, 0x110000
	v_lshl_add_u64 v[0:1], v[0:1], 0, v[148:149]
	s_mul_hi_i32 s3, s28, 0x110000
	s_add_u32 s2, s31, s2
	global_load_dwordx4 v[140:143], v[0:1], off
	global_load_dwordx4 v[136:139], v[0:1], off offset:32
	global_load_dwordx4 v[132:135], v[0:1], off offset:64
	global_load_dwordx4 v[128:131], v[0:1], off offset:96
	global_load_dwordx4 v[124:127], v[0:1], off offset:128
	global_load_dwordx4 v[120:123], v[0:1], off offset:160
	global_load_dwordx4 v[116:119], v[0:1], off offset:192
	global_load_dwordx4 v[112:115], v[0:1], off offset:224
	global_load_dwordx4 v[108:111], v[0:1], off offset:256
	global_load_dwordx4 v[104:107], v[0:1], off offset:288
	global_load_dwordx4 v[100:103], v[0:1], off offset:320
	global_load_dwordx4 v[96:99], v[0:1], off offset:352
	v_readfirstlane_b32 s0, v2
	v_mov_b32_e32 v0, v166
	s_addc_u32 s3, s33, s3
	s_lshl_b32 s0, s0, 10
	s_cmp_lg_u32 0, -1
	v_mul_hi_i32 v1, v0, s57
	v_lshrrev_b32_e32 v2, 31, v1
	v_ashrrev_i32_e32 v1, 2, v1
	s_cselect_b32 s1, 0, 0
	v_add_u32_e32 v1, v1, v2
	s_add_i32 s1, s1, s0
	v_mul_lo_u32 v2, v1, s58
	v_mul_lo_u32 v3, v1, s54
	v_lshlrev_b32_e32 v1, 3, v1
	s_add_i32 s76, s1, 0xc000
	v_add_lshl_u32 v2, v2, v0, 4
	v_and_b32_e32 v1, 0x70, v1
	v_xad_u32 v1, v2, v1, v3
	s_mov_b32 m0, s76
	s_add_i32 s77, s1, 0xe000
	v_mov_b32_e32 v240, v1
	global_load_lds_dwordx4 v1, s[4:5]
	v_add_u32_e32 v1, 0x200, v0
	v_mul_hi_i32 v2, v1, s57
	v_lshrrev_b32_e32 v3, 31, v2
	v_ashrrev_i32_e32 v2, 2, v2
	v_add_u32_e32 v2, v2, v3
	v_mul_lo_u32 v3, v2, s58
	v_add_lshl_u32 v1, v3, v1, 4
	v_mul_lo_u32 v3, v2, s54
	v_lshlrev_b32_e32 v2, 3, v2
	v_and_b32_e32 v2, 0x70, v2
	v_xad_u32 v1, v1, v2, v3
	s_mov_b32 m0, s77
	s_mov_b32 s36, 0
	v_mov_b32_e32 v241, v1
	global_load_lds_dwordx4 v1, s[4:5]
	v_add_u32_e32 v1, 0x400, v0
	v_mul_hi_i32 v2, v1, s57
	v_lshrrev_b32_e32 v3, 31, v2
	v_ashrrev_i32_e32 v2, 2, v2
	v_add_u32_e32 v2, v2, v3
	v_mul_lo_u32 v3, v2, s58
	v_add_lshl_u32 v1, v3, v1, 4
	v_mul_lo_u32 v3, v2, s54
	v_lshlrev_b32_e32 v2, 3, v2
	v_and_b32_e32 v2, 0x70, v2
	v_xad_u32 v1, v1, v2, v3
	s_add_i32 m0, s1, 0x10000
	v_bfe_u32 v2, v0, 2, 2
	v_lshrrev_b32_e32 v3, 1, v0
	v_mov_b32_e32 v242, v1
	global_load_lds_dwordx4 v1, s[4:5]
	v_lshlrev_b32_e32 v1, 4, v0
	v_and_or_b32 v2, v3, 8, v2
	v_lshlrev_b32_e32 v3, 1, v0
	v_bfe_i32 v0, v0, 4, 24
	v_and_b32_e32 v4, 0xfffff0, v0
	v_lshrrev_b32_e32 v0, 1, v0
	v_and_b32_e32 v3, 0xc0, v3
	v_and_b32_e32 v0, 4, v0
	v_and_or_b32 v3, v1, 48, v3
	v_or3_b32 v0, v4, v0, v2
	v_lshl_or_b32 v0, v0, 8, v3
	s_mov_b32 m0, s1
	s_mov_b32 s37, s36
	v_mov_b32_e32 v243, v0
	global_load_lds_dwordx4 v0, s[2:3]
	v_add_u32_e32 v0, 0x2000, v1
	v_ashrrev_i32_e32 v0, 8, v0
	v_and_b32_e32 v1, 0xfffff0, v0
	v_lshrrev_b32_e32 v0, 1, v0
	v_and_b32_e32 v0, 4, v0
	v_or3_b32 v0, v1, v0, v2
	v_lshl_or_b32 v0, v0, 8, v3
	s_add_i32 m0, s1, 0x2000
	s_add_u32 s4, s4, 0x6000
	v_mov_b32_e32 v244, v0
	global_load_lds_dwordx4 v0, s[2:3]
	v_mov_b32_e32 v0, v166
	s_waitcnt vmcnt(0)
	s_waitcnt vmcnt(0) lgkmcnt(0)
	s_barrier
	s_addc_u32 s5, s5, 0
	v_mul_hi_i32 v1, v0, s57
	v_lshrrev_b32_e32 v2, 31, v1
	v_ashrrev_i32_e32 v1, 2, v1
	v_add_u32_e32 v1, v1, v2
	v_mul_lo_u32 v2, v1, s58
	v_mul_lo_u32 v3, v1, s54
	v_lshlrev_b32_e32 v1, 3, v1
	v_add_lshl_u32 v2, v2, v0, 4
	v_and_b32_e32 v1, 0x70, v1
	s_add_i32 m0, s1, 0x12000
	v_xad_u32 v1, v2, v1, v3
	global_load_lds_dwordx4 v1, s[4:5]
	v_add_u32_e32 v1, 0x200, v0
	v_mul_hi_i32 v2, v1, s57
	v_lshrrev_b32_e32 v3, 31, v2
	v_ashrrev_i32_e32 v2, 2, v2
	v_add_u32_e32 v2, v2, v3
	v_mul_lo_u32 v3, v2, s58
	v_add_lshl_u32 v1, v3, v1, 4
	v_mul_lo_u32 v3, v2, s54
	v_lshlrev_b32_e32 v2, 3, v2
	v_and_b32_e32 v2, 0x70, v2
	v_xad_u32 v1, v1, v2, v3
	s_add_i32 m0, s1, 0x14000
	s_mov_b32 s38, s36
	global_load_lds_dwordx4 v1, s[4:5]
	v_add_u32_e32 v1, 0x400, v0
	v_mul_hi_i32 v2, v1, s57
	v_lshrrev_b32_e32 v3, 31, v2
	v_ashrrev_i32_e32 v2, 2, v2
	v_add_u32_e32 v2, v2, v3
	v_mul_lo_u32 v3, v2, s58
	v_add_lshl_u32 v1, v3, v1, 4
	v_mul_lo_u32 v3, v2, s54
	v_lshlrev_b32_e32 v2, 3, v2
	v_and_b32_e32 v2, 0x70, v2
	v_xad_u32 v1, v1, v2, v3
	s_add_i32 m0, s1, 0x16000
	v_bfe_u32 v2, v0, 2, 2
	v_lshrrev_b32_e32 v3, 1, v0
	global_load_lds_dwordx4 v1, s[4:5]
	v_lshlrev_b32_e32 v1, 4, v0
	v_and_or_b32 v2, v3, 8, v2
	v_lshlrev_b32_e32 v3, 1, v0
	v_bfe_i32 v0, v0, 4, 24
	v_and_b32_e32 v4, 0xfffff0, v0
	v_lshrrev_b32_e32 v0, 1, v0
	v_and_b32_e32 v3, 0xc0, v3
	v_and_b32_e32 v0, 4, v0
	s_add_u32 s2, s2, 0x4000
	v_and_or_b32 v3, v1, 48, v3
	v_or3_b32 v0, v4, v0, v2
	s_addc_u32 s3, s3, 0
	s_add_i32 m0, s1, 0x4000
	v_lshl_or_b32 v0, v0, 8, v3
	global_load_lds_dwordx4 v0, s[2:3]
	v_add_u32_e32 v0, 0x2000, v1
	v_ashrrev_i32_e32 v0, 8, v0
	v_and_b32_e32 v1, 0xfffff0, v0
	v_lshrrev_b32_e32 v0, 1, v0
	v_and_b32_e32 v0, 4, v0
	v_or3_b32 v0, v1, v0, v2
	v_lshl_or_b32 v0, v0, 8, v3
	s_add_i32 m0, s1, 0x6000
	s_mov_b32 s39, s36
	global_load_lds_dwordx4 v0, s[2:3]
	v_mov_b32_e32 v0, v166
	s_mov_b32 s40, s36
	v_and_b32_e32 v1, 31, v0
	v_lshlrev_b32_e32 v2, 3, v0
	v_lshrrev_b32_e32 v0, 1, v0
	v_and_b32_e32 v56, 0x70, v2
	v_mad_u32_u24 v57, v1, s54, 0
	v_and_b32_e32 v58, 16, v0
	v_xad_u32 v69, v58, v56, v57
	ds_read_b128 v[0:3], v69 offset:49152
	ds_read_b128 v[4:7], v69 offset:49280
	s_waitcnt lgkmcnt(0)
	v_mfma_f32_32x32x16_bf16 v[16:31], v[0:3], v[140:143], 0
	ds_read_b128 v[0:3], v69 offset:61440
	v_or_b32_e32 v8, 32, v58
	v_xad_u32 v70, v8, v56, v57
	ds_read_b128 v[8:11], v69 offset:49408
	v_or_b32_e32 v48, 64, v58
	v_xad_u32 v71, v48, v56, v57
	v_or_b32_e32 v58, 0x60, v58
	s_waitcnt lgkmcnt(0)
	v_mfma_f32_32x32x16_bf16 v[32:47], v[0:3], v[140:143], 0
	ds_read_b128 v[0:3], v70 offset:49152
	ds_read_b128 v[12:15], v70 offset:49280
	ds_read_b128 v[48:51], v70 offset:49408
	v_xad_u32 v72, v58, v56, v57
	s_mov_b32 s41, s36
	s_mov_b32 s42, s36
	s_mov_b32 s43, s36
	s_mov_b32 s44, s36
	s_waitcnt lgkmcnt(0)
	v_mfma_f32_32x32x16_bf16 v[16:31], v[0:3], v[136:139], v[16:31]
	ds_read_b128 v[0:3], v70 offset:61440
	s_mov_b32 s45, s36
	s_mov_b32 s46, s36
	s_mov_b32 s47, s36
	s_mov_b32 s48, s36
	s_mov_b32 s49, s36
	s_mov_b32 s50, s36
	s_waitcnt lgkmcnt(0)
	v_mfma_f32_32x32x16_bf16 v[32:47], v[0:3], v[136:139], v[32:47]
	ds_read_b128 v[0:3], v71 offset:49152
	ds_read_b128 v[52:55], v71 offset:49280
	ds_read_b128 v[56:59], v71 offset:49408
	s_mov_b32 s51, s36
	s_mov_b32 s78, -1
	v_cmp_eq_u32_e64 s[2:3], 0, v169
	v_mov_b32_e32 v170, v145
	s_waitcnt lgkmcnt(0)
	v_mfma_f32_32x32x16_bf16 v[16:31], v[0:3], v[132:135], v[16:31]
	ds_read_b128 v[0:3], v71 offset:61440
	s_waitcnt lgkmcnt(0)
	v_mfma_f32_32x32x16_bf16 v[32:47], v[0:3], v[132:135], v[32:47]
	ds_read_b128 v[0:3], v72 offset:49152
	ds_read_b128 v[60:63], v72 offset:49280
	s_waitcnt lgkmcnt(0)
	v_mfma_f32_32x32x16_bf16 v[16:31], v[0:3], v[128:131], v[16:31]
	ds_read_b128 v[0:3], v72 offset:61440
	ds_read_b128 v[64:67], v72 offset:49408
	v_mfma_f32_32x32x16_bf16 v[16:31], v[4:7], v[124:127], v[16:31]
	s_waitcnt lgkmcnt(0)
	v_mfma_f32_32x32x16_bf16 v[32:47], v[0:3], v[128:131], v[32:47]
	ds_read_b128 v[0:3], v69 offset:61568
	ds_read_b128 v[4:7], v69 offset:61696
	v_mfma_f32_32x32x16_bf16 v[16:31], v[12:15], v[120:123], v[16:31]
	s_waitcnt lgkmcnt(0)
	v_mfma_f32_32x32x16_bf16 v[32:47], v[0:3], v[124:127], v[32:47]
	ds_read_b128 v[0:3], v70 offset:61568
	ds_read_b128 v[12:15], v70 offset:61696
	v_mfma_f32_32x32x16_bf16 v[16:31], v[52:55], v[116:119], v[16:31]
	s_waitcnt lgkmcnt(0)
	v_mfma_f32_32x32x16_bf16 v[32:47], v[0:3], v[120:123], v[32:47]
	ds_read_b128 v[0:3], v71 offset:61568
	ds_read_b128 v[52:55], v71 offset:61696
	v_mfma_f32_32x32x16_bf16 v[16:31], v[60:63], v[112:115], v[16:31]
	s_waitcnt lgkmcnt(0)
	v_mfma_f32_32x32x16_bf16 v[32:47], v[0:3], v[116:119], v[32:47]
	ds_read_b128 v[0:3], v72 offset:61568
	ds_read_b128 v[60:63], v72 offset:61696
	s_waitcnt vmcnt(0)
	s_waitcnt vmcnt(0) lgkmcnt(0)
	s_barrier
	v_mfma_f32_32x32x16_bf16 v[16:31], v[8:11], v[108:111], v[16:31]
	v_mfma_f32_32x32x16_bf16 v[32:47], v[0:3], v[112:115], v[32:47]
	v_and_b32_e32 v0, 0x3fffffc0, v68
	v_lshl_add_u32 v147, v0, 2, s56
	v_lshl_add_u32 v149, v168, 2, v147
	v_mfma_f32_32x32x16_bf16 v[16:31], v[48:51], v[104:107], v[16:31]
	v_mfma_f32_32x32x16_bf16 v[32:47], v[4:7], v[108:111], v[32:47]
	v_mfma_f32_32x32x16_bf16 v[16:31], v[56:59], v[100:103], v[16:31]
	v_mfma_f32_32x32x16_bf16 v[32:47], v[12:15], v[104:107], v[32:47]
	v_mov_b64_e32 v[0:1], s[36:37]
	v_mov_b64_e32 v[2:3], s[38:39]
	v_mov_b64_e32 v[4:5], s[40:41]
	v_mov_b64_e32 v[6:7], s[42:43]
	v_mov_b64_e32 v[8:9], s[44:45]
	v_mov_b64_e32 v[10:11], s[46:47]
	v_mov_b64_e32 v[12:13], s[48:49]
	v_mfma_f32_32x32x16_bf16 v[16:31], v[64:67], v[96:99], v[16:31]
	v_mov_b64_e32 v[14:15], s[50:51]
	s_movk_i32 s46, 0x4000
	s_mov_b32 s47, 0x8000
	v_mfma_f32_32x32x16_bf16 v[32:47], v[52:55], v[100:103], v[32:47]
	s_nop 7
	v_max_f32_e32 v48, v17, v17
	v_max_f32_e32 v49, v16, v16
	v_max_f32_e32 v48, v49, v48
	v_max3_f32 v48, v48, v18, v19
	v_max3_f32 v48, v48, v20, v21
	v_max3_f32 v48, v48, v22, v23
	v_max3_f32 v48, v48, v24, v25
	v_mfma_f32_32x32x16_bf16 v[32:47], v[60:63], v[96:99], v[32:47]
	v_max3_f32 v48, v48, v26, v27
	v_max3_f32 v48, v48, v28, v29
	v_max3_f32 v48, v48, v30, v31
	s_nop 8
	v_max3_f32 v48, v48, v32, v33
	v_max3_f32 v48, v48, v34, v35
	v_max3_f32 v48, v48, v36, v37
	v_max3_f32 v48, v48, v38, v39
	v_max3_f32 v48, v48, v40, v41
	v_max3_f32 v48, v48, v42, v43
	v_max3_f32 v48, v48, v44, v45
	v_max3_f32 v48, v48, v46, v47
	v_mov_b32_e32 v49, v48
	s_nop 1
	v_permlane32_swap_b32_e32 v48, v49
	v_max_f32_e32 v49, v49, v49
	v_max_f32_e32 v48, v48, v48
	v_max_f32_e32 v48, v48, v49
	v_add_f32_e32 v49, 0x7149f2ca, v48
	v_cmp_ge_f32_e32 vcc, s63, v49
	s_cmp_eq_u64 vcc, exec
	v_max_f32_e32 v48, 0xf149f2ca, v48
	s_cselect_b64 vcc, -1, 0
	v_cndmask_b32_e32 v172, v48, v167, vcc
	v_sub_f32_e32 v49, 0xf149f2ca, v48
	v_mul_f32_e32 v48, 0xbdd53b94, v172
	v_fmamk_f32 v16, v16, 0x3dd53b94, v48
	v_exp_f32_e32 v185, v16
	v_fmamk_f32 v16, v17, 0x3dd53b94, v48
	v_exp_f32_e32 v189, v16
	v_fmamk_f32 v16, v18, 0x3dd53b94, v48
	v_exp_f32_e32 v186, v16
	v_fmamk_f32 v16, v19, 0x3dd53b94, v48
	v_exp_f32_e32 v190, v16
	v_fmamk_f32 v16, v20, 0x3dd53b94, v48
	v_exp_f32_e32 v187, v16
	v_fmamk_f32 v16, v21, 0x3dd53b94, v48
	v_exp_f32_e32 v191, v16
	v_fmamk_f32 v16, v22, 0x3dd53b94, v48
	v_exp_f32_e32 v184, v16
	v_fmamk_f32 v16, v23, 0x3dd53b94, v48
	v_exp_f32_e32 v188, v16
	v_fmamk_f32 v16, v24, 0x3dd53b94, v48
	v_mul_f32_e32 v49, 0x3dd53b94, v49
	v_exp_f32_e32 v178, v16
	v_fmamk_f32 v16, v25, 0x3dd53b94, v48
	v_exp_f32_e32 v49, v49
	v_exp_f32_e32 v182, v16
	v_fmamk_f32 v16, v26, 0x3dd53b94, v48
	v_exp_f32_e32 v179, v16
	v_fmamk_f32 v16, v27, 0x3dd53b94, v48
	v_exp_f32_e32 v183, v16
	v_fmamk_f32 v16, v28, 0x3dd53b94, v48
	v_exp_f32_e32 v176, v16
	v_fmamk_f32 v16, v29, 0x3dd53b94, v48
	s_add_i32 s4, s35, s34
	v_pk_fma_f32 v[154:155], v[46:47], s[18:19], v[48:49] op_sel_hi:[1,0,0]
	v_pk_fma_f32 v[158:159], v[44:45], s[18:19], v[48:49] op_sel_hi:[1,0,0]
	v_pk_fma_f32 v[164:165], v[42:43], s[18:19], v[48:49] op_sel_hi:[1,0,0]
	v_pk_fma_f32 v[150:151], v[40:41], s[18:19], v[48:49] op_sel_hi:[1,0,0]
	v_pk_fma_f32 v[152:153], v[38:39], s[18:19], v[48:49] op_sel_hi:[1,0,0]
	v_pk_fma_f32 v[156:157], v[36:37], s[18:19], v[48:49] op_sel_hi:[1,0,0]
	v_pk_fma_f32 v[160:161], v[34:35], s[18:19], v[48:49] op_sel_hi:[1,0,0]
	v_pk_fma_f32 v[162:163], v[32:33], s[18:19], v[48:49] op_sel_hi:[1,0,0]
	v_exp_f32_e32 v180, v16
	v_fmamk_f32 v16, v30, 0x3dd53b94, v48
	v_fmac_f32_e32 v48, 0x3dd53b94, v31
	s_mul_i32 s34, s4, 0x110000
	v_exp_f32_e32 v177, v16
	v_exp_f32_e32 v181, v48
	s_mul_hi_i32 s5, s4, 0x110000
	s_add_u32 s41, s86, s34
	s_addc_u32 s42, s87, s5
	s_mul_hi_i32 s5, s4, 0x198000
	s_mul_i32 s4, s4, 0x198000
	v_cndmask_b32_e64 v171, v49, 1.0, vcc
	s_add_u32 s43, s86, s4
	v_mov_b64_e32 v[62:63], v[14:15]
	v_mov_b64_e32 v[46:47], v[14:15]
	v_mov_b64_e32 v[30:31], v[14:15]
	s_addc_u32 s44, s87, s5
	s_add_i32 s45, s76, 0x4000
	v_mov_b64_e32 v[60:61], v[12:13]
	v_mov_b64_e32 v[58:59], v[10:11]
	v_mov_b64_e32 v[56:57], v[8:9]
	v_mov_b64_e32 v[54:55], v[6:7]
	v_mov_b64_e32 v[52:53], v[4:5]
	v_mov_b64_e32 v[50:51], v[2:3]
	v_mov_b64_e32 v[48:49], v[0:1]
	v_mov_b64_e32 v[44:45], v[12:13]
	v_mov_b64_e32 v[42:43], v[10:11]
	v_mov_b64_e32 v[40:41], v[8:9]
	v_mov_b64_e32 v[38:39], v[6:7]
	v_mov_b64_e32 v[36:37], v[4:5]
	v_mov_b64_e32 v[34:35], v[2:3]
	v_mov_b64_e32 v[32:33], v[0:1]
	v_mov_b64_e32 v[28:29], v[12:13]
	v_mov_b64_e32 v[26:27], v[10:11]
	v_mov_b64_e32 v[24:25], v[8:9]
	v_mov_b64_e32 v[22:23], v[6:7]
	v_mov_b64_e32 v[20:21], v[4:5]
	v_mov_b64_e32 v[18:19], v[2:3]
	v_mov_b64_e32 v[16:17], v[0:1]
	v_and_b32_e32 v65, 31, v166
	v_lshlrev_b32_e32 v66, 3, v166
	v_and_b32_e32 v66, 0x70, v66
	v_lshrrev_b32_e32 v64, 1, v166
	v_and_b32_e32 v64, 16, v64
	s_movk_i32 s98, 0x6000
	v_mov_b32_e32 v67, s98
	v_mad_u32_u24 v65, v65, s54, v67
	v_xad_u32 v246, v64, v66, v65
	v_or_b32_e32 v67, 32, v64
	v_xad_u32 v247, v67, v66, v65
	v_or_b32_e32 v67, 64, v64
	v_xad_u32 v248, v67, v66, v65
	v_or_b32_e32 v67, 0x60, v64
	v_xad_u32 v249, v67, v66, v65
	v_lshlrev_b32_e32 v64, 3, v166
	v_lshlrev_b32_e32 v65, 4, v166
	v_lshlrev_b32_e32 v66, 1, v166
	v_and_b32_e32 v67, 24, v64
	v_and_b32_e32 v65, 0xc0, v65
	v_and_b32_e32 v66, 32, v66
	v_or3_b32 v66, v67, v65, v66
	v_and_b32_e32 v64, 0x100, v64
	v_add_u32_e32 v250, v64, v66
.LBB0_1098:
	s_add_u32 s34, s43, s16
	s_addc_u32 s35, s44, s17
	s_mov_b32 m0, s76
	s_add_u32 s98, s34, s20
	s_addc_u32 s99, s35, s21
	global_load_lds_dwordx4 v240, s[98:99]
	s_mov_b32 m0, s77
	s_nop 0
	global_load_lds_dwordx4 v241, s[98:99]
	s_mov_b32 m0, s45
	s_nop 0
	global_load_lds_dwordx4 v242, s[98:99]
	s_add_i32 s4, s1, s47
	s_add_u32 s38, s41, s16
	s_addc_u32 s39, s42, s17
	s_mov_b32 m0, s4
	s_mov_b32 s48, s46
	s_add_u32 s100, s38, s22
	s_addc_u32 s101, s39, s23
	global_load_lds_dwordx4 v243, s[100:101]
	s_add_i32 m0, s4, 0x2000
	s_mov_b32 s46, s36
	global_load_lds_dwordx4 v244, s[100:101]
	ds_read_b128 v[64:67], v246 offset:49152
	ds_read_b128 v[68:71], v246 offset:61440
	ds_read_b128 v[232:235], v247 offset:49152
	ds_read_b128 v[236:239], v247 offset:61440
	ds_read_b128 v[200:203], v248 offset:49152
	ds_read_b128 v[204:207], v248 offset:61440
	s_add_i32 s49, 0, 0x12000
	s_waitcnt lgkmcnt(4)
	v_mfma_f32_32x32x16_bf16 v[80:95], v[64:67], v[140:143], 0
	v_mfma_f32_32x32x16_bf16 v[64:79], v[68:71], v[140:143], 0
	ds_read_b128 v[216:219], v249 offset:49152
	ds_read_b128 v[220:223], v249 offset:61440
	v_exp_f32_e32 v160, v160
	v_exp_f32_e32 v161, v161
	v_exp_f32_e32 v164, v164
	s_waitcnt lgkmcnt(4)
	v_mfma_f32_32x32x16_bf16 v[80:95], v[232:235], v[136:139], v[80:95]
	v_exp_f32_e32 v165, v165
	v_mfma_f32_32x32x16_bf16 v[64:79], v[236:239], v[136:139], v[64:79]
	ds_read_b128 v[232:235], v246 offset:49280
	ds_read_b128 v[236:239], v246 offset:61568
	s_waitcnt lgkmcnt(4)
	v_mfma_f32_32x32x16_bf16 v[80:95], v[200:203], v[132:135], v[80:95]
	v_mfma_f32_32x32x16_bf16 v[64:79], v[204:207], v[132:135], v[64:79]
	ds_read_b128 v[200:203], v247 offset:49280
	ds_read_b128 v[204:207], v247 offset:61568
	s_waitcnt lgkmcnt(4)
	v_mfma_f32_32x32x16_bf16 v[80:95], v[216:219], v[128:131], v[80:95]
	v_mfma_f32_32x32x16_bf16 v[64:79], v[220:223], v[128:131], v[64:79]
	ds_read_b128 v[216:219], v248 offset:49280
	ds_read_b128 v[220:223], v248 offset:61568
	s_waitcnt lgkmcnt(4)
	v_mfma_f32_32x32x16_bf16 v[80:95], v[232:235], v[124:127], v[80:95]
	v_exp_f32_e32 v175, v157
	v_mfma_f32_32x32x16_bf16 v[64:79], v[236:239], v[124:127], v[64:79]
	ds_read_b128 v[232:235], v249 offset:49280
	ds_read_b128 v[236:239], v249 offset:61568
	s_waitcnt lgkmcnt(4)
	v_mfma_f32_32x32x16_bf16 v[80:95], v[200:203], v[120:123], v[80:95]
	v_mfma_f32_32x32x16_bf16 v[64:79], v[204:207], v[120:123], v[64:79]
	ds_read_b128 v[200:203], v246 offset:49408
	ds_read_b128 v[204:207], v246 offset:61696
	v_exp_f32_e32 v144, v162
	v_exp_f32_e32 v162, v163
	v_exp_f32_e32 v163, v156
	s_waitcnt lgkmcnt(4)
	v_mfma_f32_32x32x16_bf16 v[80:95], v[216:219], v[116:119], v[80:95]
	v_exp_f32_e32 v214, v150
	v_add_f32_e32 v150, 0, v185
	v_add_f32_e32 v150, v189, v150
	v_add_f32_e32 v150, v186, v150
	v_add_f32_e32 v150, v190, v150
	v_add_f32_e32 v150, v187, v150
	v_add_f32_e32 v150, v191, v150
	v_mfma_f32_32x32x16_bf16 v[64:79], v[220:223], v[116:119], v[64:79]
	ds_read_b128 v[216:219], v247 offset:49408
	ds_read_b128 v[220:223], v247 offset:61696
	v_add_f32_e32 v150, v184, v150
	v_add_f32_e32 v150, v188, v150
	v_add_f32_e32 v150, v178, v150
	v_add_f32_e32 v150, v182, v150
	v_add_f32_e32 v150, v179, v150
	v_add_f32_e32 v150, v183, v150
	v_add_f32_e32 v150, v176, v150
	s_waitcnt lgkmcnt(4)
	v_mfma_f32_32x32x16_bf16 v[80:95], v[232:235], v[112:115], v[80:95]
	v_add_f32_e32 v150, v180, v150
	v_add_f32_e32 v150, v177, v150
	v_add_f32_e32 v150, v181, v150
	v_add_f32_e32 v150, v144, v150
	v_add_f32_e32 v150, v162, v150
	v_exp_f32_e32 v212, v152
	v_add_f32_e32 v150, v160, v150
	v_mfma_f32_32x32x16_bf16 v[64:79], v[236:239], v[112:115], v[64:79]
	ds_read_b128 v[232:235], v248 offset:49408
	ds_read_b128 v[236:239], v248 offset:61696
	v_exp_f32_e32 v213, v153
	v_add_f32_e32 v150, v161, v150
	v_add_f32_e32 v150, v163, v150
	v_exp_f32_e32 v215, v151
	v_add_f32_e32 v150, v175, v150
	v_add_f32_e32 v150, v212, v150
	v_add_f32_e32 v150, v213, v150
	s_waitcnt lgkmcnt(4)
	v_mfma_f32_32x32x16_bf16 v[80:95], v[200:203], v[108:111], v[80:95]
	v_exp_f32_e32 v228, v158
	v_add_f32_e32 v150, v214, v150
	v_exp_f32_e32 v229, v159
	v_add_f32_e32 v150, v215, v150
	v_exp_f32_e32 v230, v154
	v_add_f32_e32 v150, v164, v150
	v_exp_f32_e32 v231, v155
	v_mfma_f32_32x32x16_bf16 v[64:79], v[204:207], v[108:111], v[64:79]
	ds_read_b128 v[200:203], v249 offset:49408
	ds_read_b128 v[204:207], v249 offset:61696
	v_add_f32_e32 v150, v165, v150
	v_add_f32_e32 v150, v228, v150
	v_add_f32_e32 v150, v229, v150
	v_add_f32_e32 v150, v230, v150
	v_add_f32_e32 v173, v231, v150
	v_mov_b32_e32 v174, v173
	s_nop 1
	v_permlane32_swap_b32_e32 v173, v174
	s_waitcnt lgkmcnt(4)
	v_mfma_f32_32x32x16_bf16 v[80:95], v[216:219], v[104:107], v[80:95]
	v_cvt_pk_bf16_f32 v150, v185, v189
	v_cvt_pk_bf16_f32 v151, v186, v190
	v_cvt_pk_bf16_f32 v152, v187, v191
	v_cvt_pk_bf16_f32 v153, v184, v188
	v_cvt_pk_bf16_f32 v154, v178, v182
	v_cvt_pk_bf16_f32 v155, v179, v183
	v_cvt_pk_bf16_f32 v156, v176, v180
	v_mfma_f32_32x32x16_bf16 v[64:79], v[220:223], v[104:107], v[64:79]
	v_cvt_pk_bf16_f32 v157, v177, v181
	v_cvt_pk_bf16_f32 v158, v144, v162
	v_cvt_pk_bf16_f32 v159, v160, v161
	v_cvt_pk_bf16_f32 v160, v163, v175
	v_cvt_pk_bf16_f32 v161, v212, v213
	v_cvt_pk_bf16_f32 v162, v214, v215
	v_cvt_pk_bf16_f32 v163, v164, v165
	s_waitcnt lgkmcnt(2)
	v_mfma_f32_32x32x16_bf16 v[80:95], v[232:235], v[100:103], v[80:95]
	v_cvt_pk_bf16_f32 v164, v228, v229
	v_cvt_pk_bf16_f32 v165, v230, v231
	v_permlane32_swap_b32_e32 v150, v152
	v_permlane32_swap_b32_e32 v151, v153
	v_permlane32_swap_b32_e32 v154, v156
	v_mfma_f32_32x32x16_bf16 v[64:79], v[236:239], v[100:103], v[64:79]
	v_permlane32_swap_b32_e32 v155, v157
	v_permlane32_swap_b32_e32 v158, v160
	v_permlane32_swap_b32_e32 v159, v161
	v_permlane32_swap_b32_e32 v162, v164
	s_waitcnt lgkmcnt(0)
	v_mfma_f32_32x32x16_bf16 v[80:95], v[200:203], v[96:99], v[80:95]
	v_permlane32_swap_b32_e32 v163, v165
	v_mfma_f32_32x32x16_bf16 v[64:79], v[204:207], v[96:99], v[64:79]
	s_cmp_lg_u32 0, -1
	s_cselect_b32 s4, 0, 0
	s_add_i32 s40, s36, s4
	v_add_u32_e32 v144, s40, v250
	ds_read_b64_tr_b16 v[176:177], v144 offset:0
	ds_read_b64_tr_b16 v[178:179], v144 offset:0x800
	ds_read_b64_tr_b16 v[180:181], v144 offset:0x1000
	ds_read_b64_tr_b16 v[182:183], v144 offset:0x1800
	ds_read_b64_tr_b16 v[184:185], v144 offset:0x2000
	ds_read_b64_tr_b16 v[186:187], v144 offset:0x2800
	ds_read_b64_tr_b16 v[188:189], v144 offset:0x3000
	ds_read_b64_tr_b16 v[190:191], v144 offset:0x3800
	s_waitcnt lgkmcnt(0)
	s_nop 0
	v_mfma_f32_32x32x16_bf16 v[0:15], v[150:153], v[176:179], v[0:15]
	ds_read_b64_tr_b16 v[176:177], v144 offset:0x200
	ds_read_b64_tr_b16 v[178:179], v144 offset:0xa00
	v_mfma_f32_32x32x16_bf16 v[0:15], v[154:157], v[180:183], v[0:15]
	ds_read_b64_tr_b16 v[180:181], v144 offset:0x1200
	ds_read_b64_tr_b16 v[182:183], v144 offset:0x1a00
	v_mfma_f32_32x32x16_bf16 v[0:15], v[158:161], v[184:187], v[0:15]
	ds_read_b64_tr_b16 v[184:185], v144 offset:0x2200
	ds_read_b64_tr_b16 v[186:187], v144 offset:0x2a00
	ds_read_b64_tr_b16 v[192:193], v144 offset:0x3200
	ds_read_b64_tr_b16 v[194:195], v144 offset:0x3a00
	s_waitcnt lgkmcnt(0)
	v_mfma_f32_32x32x16_bf16 v[0:15], v[162:165], v[188:191], v[0:15]
	v_mfma_f32_32x32x16_bf16 v[48:63], v[150:153], v[176:179], v[48:63]
	ds_read_b64_tr_b16 v[176:177], v144 offset:0x400
	ds_read_b64_tr_b16 v[178:179], v144 offset:0xc00
	v_mfma_f32_32x32x16_bf16 v[48:63], v[154:157], v[180:183], v[48:63]
	ds_read_b64_tr_b16 v[180:181], v144 offset:0x1400
	ds_read_b64_tr_b16 v[182:183], v144 offset:0x1c00
	v_mfma_f32_32x32x16_bf16 v[48:63], v[158:161], v[184:187], v[48:63]
	ds_read_b64_tr_b16 v[184:185], v144 offset:0x2400
	ds_read_b64_tr_b16 v[186:187], v144 offset:0x2c00
	ds_read_b64_tr_b16 v[188:189], v144 offset:0x3400
	ds_read_b64_tr_b16 v[190:191], v144 offset:0x3c00
	s_waitcnt lgkmcnt(0)
	v_mfma_f32_32x32x16_bf16 v[48:63], v[162:165], v[192:195], v[48:63]
	v_mfma_f32_32x32x16_bf16 v[32:47], v[150:153], v[176:179], v[32:47]
	ds_read_b64_tr_b16 v[176:177], v144 offset:0x600
	ds_read_b64_tr_b16 v[178:179], v144 offset:0xe00
	v_mfma_f32_32x32x16_bf16 v[32:47], v[154:157], v[180:183], v[32:47]
	ds_read_b64_tr_b16 v[180:181], v144 offset:0x1600
	ds_read_b64_tr_b16 v[182:183], v144 offset:0x1e00
	v_mfma_f32_32x32x16_bf16 v[32:47], v[158:161], v[184:187], v[32:47]
	ds_read_b64_tr_b16 v[184:185], v144 offset:0x2600
	ds_read_b64_tr_b16 v[186:187], v144 offset:0x2e00
	ds_read_b64_tr_b16 v[192:193], v144 offset:0x3600
	ds_read_b64_tr_b16 v[194:195], v144 offset:0x3e00
	s_waitcnt lgkmcnt(0)
	v_mfma_f32_32x32x16_bf16 v[32:47], v[162:165], v[188:191], v[32:47]
	v_mfma_f32_32x32x16_bf16 v[16:31], v[150:153], v[176:179], v[16:31]
	v_max_f32_e32 v144, v81, v81
	v_max_f32_e32 v175, v80, v80
	v_max_f32_e32 v144, v175, v144
	v_max3_f32 v144, v144, v82, v83
	v_max3_f32 v144, v144, v84, v85
	v_max3_f32 v144, v144, v86, v87
	v_max3_f32 v144, v144, v88, v89
	v_max3_f32 v144, v144, v90, v91
	v_mfma_f32_32x32x16_bf16 v[16:31], v[154:157], v[180:183], v[16:31]
	v_max3_f32 v144, v144, v92, v93
	v_max3_f32 v144, v144, v94, v95
	v_max3_f32 v144, v144, v64, v65
	v_max3_f32 v144, v144, v66, v67
	v_max3_f32 v144, v144, v68, v69
	v_max3_f32 v144, v144, v70, v71
	v_max3_f32 v144, v144, v72, v73
	v_max3_f32 v144, v144, v74, v75
	v_mfma_f32_32x32x16_bf16 v[16:31], v[158:161], v[184:187], v[16:31]
	v_max3_f32 v144, v144, v76, v77
	v_max3_f32 v144, v144, v78, v79
	v_mov_b32_e32 v150, v144
	s_nop 1
	v_permlane32_swap_b32_e32 v144, v150
	v_max_f32_e32 v150, v150, v150
	v_max_f32_e32 v144, v144, v144
	v_max_f32_e32 v144, v144, v150
	v_max_f32_e32 v151, v172, v172
	v_sub_f32_e32 v150, v144, v172
	v_max_f32_e32 v144, v151, v144
	v_mfma_f32_32x32x16_bf16 v[16:31], v[162:165], v[192:195], v[16:31]
	v_sub_f32_e32 v151, v172, v144
	v_mul_f32_e32 v151, 0x3dd53b94, v151
	v_exp_f32_e32 v151, v151
	v_cmp_ge_f32_e32 vcc, s63, v150
	s_cmp_eq_u64 vcc, exec
	s_cselect_b64 s[4:5], -1, 0
	s_waitcnt vmcnt(0)
	v_cndmask_b32_e64 v175, v151, 1.0, s[4:5]
	v_cmp_gt_f32_e32 vcc, 1.0, v175
	s_waitcnt vmcnt(0)
	s_barrier
	s_cbranch_vccz .LBB0_1102
	s_and_saveexec_b64 s[36:37], s[2:3]
	ds_write_b32 v149, v175 offset:128
	s_or_b64 exec, exec, s[36:37]
	s_waitcnt lgkmcnt(0)
	v_add_u32_e32 v162, v147, v148
	ds_read_b128 v[150:153], v162 offset:224
	ds_read_b128 v[154:157], v162 offset:192
	ds_read_b128 v[158:161], v162 offset:160
	ds_read_b128 v[162:165], v162 offset:128
	s_waitcnt lgkmcnt(3)
	v_pk_mul_f32 v[12:13], v[12:13], v[150:151]
	s_waitcnt lgkmcnt(2)
	v_pk_mul_f32 v[8:9], v[8:9], v[154:155]
	s_waitcnt lgkmcnt(1)
	v_pk_mul_f32 v[4:5], v[4:5], v[158:159]
	v_pk_mul_f32 v[14:15], v[14:15], v[152:153]
	v_pk_mul_f32 v[10:11], v[10:11], v[156:157]
	v_pk_mul_f32 v[6:7], v[6:7], v[160:161]
	s_waitcnt lgkmcnt(0)
	v_pk_mul_f32 v[2:3], v[2:3], v[164:165]
	v_pk_mul_f32 v[0:1], v[0:1], v[162:163]
	v_pk_mul_f32 v[60:61], v[60:61], v[150:151]
	v_pk_mul_f32 v[56:57], v[56:57], v[154:155]
	v_pk_mul_f32 v[52:53], v[52:53], v[158:159]
	v_pk_mul_f32 v[62:63], v[62:63], v[152:153]
	v_pk_mul_f32 v[58:59], v[58:59], v[156:157]
	v_pk_mul_f32 v[54:55], v[54:55], v[160:161]
	v_pk_mul_f32 v[50:51], v[50:51], v[164:165]
	v_pk_mul_f32 v[48:49], v[48:49], v[162:163]
	v_pk_mul_f32 v[44:45], v[44:45], v[150:151]
	v_pk_mul_f32 v[40:41], v[40:41], v[154:155]
	v_pk_mul_f32 v[36:37], v[36:37], v[158:159]
	v_pk_mul_f32 v[46:47], v[46:47], v[152:153]
	v_pk_mul_f32 v[42:43], v[42:43], v[156:157]
	v_pk_mul_f32 v[38:39], v[38:39], v[160:161]
	v_pk_mul_f32 v[34:35], v[34:35], v[164:165]
	v_pk_mul_f32 v[32:33], v[32:33], v[162:163]
	v_pk_mul_f32 v[28:29], v[28:29], v[150:151]
	v_pk_mul_f32 v[24:25], v[24:25], v[154:155]
	v_pk_mul_f32 v[20:21], v[20:21], v[158:159]
	v_pk_mul_f32 v[30:31], v[30:31], v[152:153]
	v_pk_mul_f32 v[26:27], v[26:27], v[156:157]
	v_pk_mul_f32 v[22:23], v[22:23], v[160:161]
	v_pk_mul_f32 v[18:19], v[18:19], v[164:165]
	v_pk_mul_f32 v[16:17], v[16:17], v[162:163]
.LBB0_1102:
	v_cndmask_b32_e64 v150, v144, v172, s[4:5]
	v_mul_f32_e32 v176, 0xbdd53b94, v150
	v_fmamk_f32 v187, v66, 0x3dd53b94, v176
	v_fmamk_f32 v185, v64, 0x3dd53b94, v176
	v_fmamk_f32 v186, v65, 0x3dd53b94, v176
	v_fmamk_f32 v188, v67, 0x3dd53b94, v176
	s_cmp_lg_u32 0, -1
	s_cselect_b32 s4, 0, 0
	s_add_i32 s5, s4, s0
	s_add_i32 m0, s5, 0x12000
	v_fmamk_f32 v178, v69, 0x3dd53b94, v176
	s_add_u32 s98, s34, s24
	s_addc_u32 s99, s35, s25
	global_load_lds_dwordx4 v240, s[98:99]
	s_add_i32 m0, s5, 0x14000
	v_fmamk_f32 v179, v70, 0x3dd53b94, v176
	global_load_lds_dwordx4 v241, s[98:99]
	s_add_i32 m0, s5, 0x16000
	v_fmamk_f32 v189, v68, 0x3dd53b94, v176
	global_load_lds_dwordx4 v242, s[98:99]
	v_fmamk_f32 v180, v71, 0x3dd53b94, v176
	s_add_i32 s5, s1, s46
	s_mov_b32 m0, s5
	v_fmamk_f32 v94, v94, 0x3dd53b94, v176
	s_add_u32 s100, s38, s26
	s_addc_u32 s101, s39, s27
	global_load_lds_dwordx4 v243, s[100:101]
	s_add_i32 m0, s5, 0x2000
	v_exp_f32_e32 v151, v94
	global_load_lds_dwordx4 v244, s[100:101]
	v_fmamk_f32 v80, v80, 0x3dd53b94, v176
	v_fmamk_f32 v81, v81, 0x3dd53b94, v176
	v_fmamk_f32 v82, v82, 0x3dd53b94, v176
	v_fmamk_f32 v83, v83, 0x3dd53b94, v176
	v_fmamk_f32 v84, v84, 0x3dd53b94, v176
	v_fmamk_f32 v85, v85, 0x3dd53b94, v176
	v_fmamk_f32 v86, v86, 0x3dd53b94, v176
	v_fmamk_f32 v87, v87, 0x3dd53b94, v176
	v_fmamk_f32 v88, v88, 0x3dd53b94, v176
	v_fmamk_f32 v89, v89, 0x3dd53b94, v176
	v_fmamk_f32 v90, v90, 0x3dd53b94, v176
	v_fmamk_f32 v91, v91, 0x3dd53b94, v176
	v_fmamk_f32 v92, v92, 0x3dd53b94, v176
	v_fmamk_f32 v93, v93, 0x3dd53b94, v176
	v_fmamk_f32 v95, v95, 0x3dd53b94, v176
	v_fmamk_f32 v181, v72, 0x3dd53b94, v176
	v_fmamk_f32 v182, v73, 0x3dd53b94, v176
	v_fmamk_f32 v183, v74, 0x3dd53b94, v176
	v_fmamk_f32 v184, v75, 0x3dd53b94, v176
	v_fmamk_f32 v177, v76, 0x3dd53b94, v176
	v_exp_f32_e32 v164, v80
	v_exp_f32_e32 v172, v81
	v_exp_f32_e32 v162, v82
	v_exp_f32_e32 v165, v83
	v_exp_f32_e32 v161, v84
	v_exp_f32_e32 v163, v85
	v_exp_f32_e32 v159, v86
	v_exp_f32_e32 v160, v87
	v_exp_f32_e32 v156, v88
	v_exp_f32_e32 v158, v89
	v_exp_f32_e32 v155, v90
	v_exp_f32_e32 v157, v91
	v_exp_f32_e32 v152, v92
	v_exp_f32_e32 v154, v93
	v_exp_f32_e32 v153, v95
	v_fmamk_f32 v190, v77, 0x3dd53b94, v176
	v_fmamk_f32 v191, v78, 0x3dd53b94, v176
	v_fmac_f32_e32 v176, 0x3dd53b94, v79
	ds_read_b128 v[64:67], v246 offset:24576
	ds_read_b128 v[68:71], v246 offset:36864
	ds_read_b128 v[232:235], v247 offset:24576
	ds_read_b128 v[236:239], v247 offset:36864
	ds_read_b128 v[200:203], v248 offset:24576
	ds_read_b128 v[204:207], v248 offset:36864
	v_exp_f32_e32 v180, v180
	s_waitcnt lgkmcnt(4)
	v_mfma_f32_32x32x16_bf16 v[80:95], v[64:67], v[140:143], 0
	v_mfma_f32_32x32x16_bf16 v[64:79], v[68:71], v[140:143], 0
	ds_read_b128 v[216:219], v249 offset:24576
	ds_read_b128 v[220:223], v249 offset:36864
	v_exp_f32_e32 v181, v181
	v_exp_f32_e32 v182, v182
	v_exp_f32_e32 v183, v183
	s_waitcnt lgkmcnt(4)
	v_mfma_f32_32x32x16_bf16 v[80:95], v[232:235], v[136:139], v[80:95]
	v_exp_f32_e32 v184, v184
	v_exp_f32_e32 v190, v190
	v_exp_f32_e32 v191, v191
	v_mfma_f32_32x32x16_bf16 v[64:79], v[236:239], v[136:139], v[64:79]
	ds_read_b128 v[232:235], v246 offset:24704
	ds_read_b128 v[236:239], v246 offset:36992
	s_waitcnt lgkmcnt(4)
	v_mfma_f32_32x32x16_bf16 v[80:95], v[200:203], v[132:135], v[80:95]
	v_mfma_f32_32x32x16_bf16 v[64:79], v[204:207], v[132:135], v[64:79]
	ds_read_b128 v[200:203], v247 offset:24704
	ds_read_b128 v[204:207], v247 offset:36992
	s_waitcnt lgkmcnt(4)
	v_mfma_f32_32x32x16_bf16 v[80:95], v[216:219], v[128:131], v[80:95]
	v_mfma_f32_32x32x16_bf16 v[64:79], v[220:223], v[128:131], v[64:79]
	ds_read_b128 v[216:219], v248 offset:24704
	ds_read_b128 v[220:223], v248 offset:36992
	s_waitcnt lgkmcnt(4)
	v_mfma_f32_32x32x16_bf16 v[80:95], v[232:235], v[124:127], v[80:95]
	v_mfma_f32_32x32x16_bf16 v[64:79], v[236:239], v[124:127], v[64:79]
	ds_read_b128 v[232:235], v249 offset:24704
	ds_read_b128 v[236:239], v249 offset:36992
	s_waitcnt lgkmcnt(4)
	v_mfma_f32_32x32x16_bf16 v[80:95], v[200:203], v[120:123], v[80:95]
	v_mfma_f32_32x32x16_bf16 v[64:79], v[204:207], v[120:123], v[64:79]
	ds_read_b128 v[200:203], v246 offset:24832
	ds_read_b128 v[204:207], v246 offset:37120
	v_exp_f32_e32 v144, v185
	v_exp_f32_e32 v185, v186
	v_exp_f32_e32 v186, v187
	v_exp_f32_e32 v187, v188
	v_exp_f32_e32 v188, v189
	v_exp_f32_e32 v189, v178
	s_waitcnt lgkmcnt(4)
	v_mfma_f32_32x32x16_bf16 v[80:95], v[216:219], v[116:119], v[80:95]
	v_exp_f32_e32 v214, v176
	v_add_f32_e32 v176, 0, v164
	v_add_f32_e32 v176, v172, v176
	v_add_f32_e32 v176, v162, v176
	v_add_f32_e32 v176, v165, v176
	v_add_f32_e32 v176, v161, v176
	v_add_f32_e32 v176, v163, v176
	v_mfma_f32_32x32x16_bf16 v[64:79], v[220:223], v[116:119], v[64:79]
	ds_read_b128 v[216:219], v247 offset:24832
	ds_read_b128 v[220:223], v247 offset:37120
	v_add_f32_e32 v176, v159, v176
	v_add_f32_e32 v176, v160, v176
	v_add_f32_e32 v176, v156, v176
	v_add_f32_e32 v176, v158, v176
	v_add_f32_e32 v176, v155, v176
	v_add_f32_e32 v176, v157, v176
	v_add_f32_e32 v176, v152, v176
	s_waitcnt lgkmcnt(4)
	v_mfma_f32_32x32x16_bf16 v[80:95], v[232:235], v[112:115], v[80:95]
	v_add_f32_e32 v176, v154, v176
	v_add_f32_e32 v176, v151, v176
	v_add_f32_e32 v176, v153, v176
	v_add_f32_e32 v176, v144, v176
	v_add_f32_e32 v176, v185, v176
	v_exp_f32_e32 v212, v179
	v_add_f32_e32 v176, v186, v176
	v_mfma_f32_32x32x16_bf16 v[64:79], v[236:239], v[112:115], v[64:79]
	ds_read_b128 v[232:235], v248 offset:24832
	ds_read_b128 v[236:239], v248 offset:37120
	v_add_f32_e32 v176, v187, v176
	v_add_f32_e32 v176, v188, v176
	v_add_f32_e32 v176, v189, v176
	v_add_f32_e32 v176, v212, v176
	v_add_f32_e32 v176, v180, v176
	v_exp_f32_e32 v213, v177
	v_add_f32_e32 v176, v181, v176
	s_waitcnt lgkmcnt(4)
	v_mfma_f32_32x32x16_bf16 v[80:95], v[200:203], v[108:111], v[80:95]
	v_add_f32_e32 v176, v182, v176
	v_add_f32_e32 v176, v183, v176
	v_add_f32_e32 v176, v184, v176
	v_add_f32_e32 v176, v213, v176
	v_add_f32_e32 v176, v190, v176
	v_add_f32_e32 v176, v191, v176
	v_add_f32_e32 v192, v214, v176
	v_mfma_f32_32x32x16_bf16 v[64:79], v[204:207], v[108:111], v[64:79]
	ds_read_b128 v[200:203], v249 offset:24832
	ds_read_b128 v[204:207], v249 offset:37120
	v_mov_b32_e32 v193, v192
	s_nop 1
	v_permlane32_swap_b32_e32 v192, v193
	v_cvt_pk_bf16_f32 v176, v164, v172
	v_cvt_pk_bf16_f32 v177, v162, v165
	v_cvt_pk_bf16_f32 v178, v161, v163
	v_cvt_pk_bf16_f32 v179, v159, v160
	s_waitcnt lgkmcnt(4)
	v_mfma_f32_32x32x16_bf16 v[80:95], v[216:219], v[104:107], v[80:95]
	v_cvt_pk_bf16_f32 v156, v156, v158
	v_cvt_pk_bf16_f32 v157, v155, v157
	v_cvt_pk_bf16_f32 v158, v152, v154
	v_cvt_pk_bf16_f32 v159, v151, v153
	v_cvt_pk_bf16_f32 v152, v144, v185
	v_cvt_pk_bf16_f32 v153, v186, v187
	v_cvt_pk_bf16_f32 v154, v188, v189
	v_mfma_f32_32x32x16_bf16 v[64:79], v[220:223], v[104:107], v[64:79]
	v_cvt_pk_bf16_f32 v155, v212, v180
	v_cvt_pk_bf16_f32 v160, v181, v182
	v_cvt_pk_bf16_f32 v161, v183, v184
	v_cvt_pk_bf16_f32 v162, v213, v190
	v_cvt_pk_bf16_f32 v163, v191, v214
	v_permlane32_swap_b32_e32 v176, v178
	s_waitcnt lgkmcnt(2)
	v_mfma_f32_32x32x16_bf16 v[80:95], v[232:235], v[100:103], v[80:95]
	v_permlane32_swap_b32_e32 v177, v179
	v_permlane32_swap_b32_e32 v156, v158
	v_permlane32_swap_b32_e32 v157, v159
	v_permlane32_swap_b32_e32 v152, v154
	v_mfma_f32_32x32x16_bf16 v[64:79], v[236:239], v[100:103], v[64:79]
	v_permlane32_swap_b32_e32 v153, v155
	v_permlane32_swap_b32_e32 v160, v162
	v_permlane32_swap_b32_e32 v161, v163
	s_waitcnt lgkmcnt(0)
	v_mfma_f32_32x32x16_bf16 v[80:95], v[200:203], v[96:99], v[80:95]
	v_mfma_f32_32x32x16_bf16 v[64:79], v[204:207], v[96:99], v[64:79]
	s_add_i32 s4, s48, s4
	v_add_u32_e32 v144, s4, v250
	ds_read_b64_tr_b16 v[180:181], v144 offset:0
	ds_read_b64_tr_b16 v[182:183], v144 offset:0x800
	ds_read_b64_tr_b16 v[184:185], v144 offset:0x1000
	ds_read_b64_tr_b16 v[186:187], v144 offset:0x1800
	ds_read_b64_tr_b16 v[188:189], v144 offset:0x2000
	ds_read_b64_tr_b16 v[190:191], v144 offset:0x2800
	ds_read_b64_tr_b16 v[194:195], v144 offset:0x3000
	ds_read_b64_tr_b16 v[196:197], v144 offset:0x3800
	s_waitcnt lgkmcnt(0)
	s_nop 0
	v_mfma_f32_32x32x16_bf16 v[0:15], v[176:179], v[180:183], v[0:15]
	ds_read_b64_tr_b16 v[180:181], v144 offset:0x200
	ds_read_b64_tr_b16 v[182:183], v144 offset:0xa00
	v_mfma_f32_32x32x16_bf16 v[0:15], v[156:159], v[184:187], v[0:15]
	ds_read_b64_tr_b16 v[184:185], v144 offset:0x1200
	ds_read_b64_tr_b16 v[186:187], v144 offset:0x1a00
	v_mfma_f32_32x32x16_bf16 v[0:15], v[152:155], v[188:191], v[0:15]
	ds_read_b64_tr_b16 v[188:189], v144 offset:0x2200
	ds_read_b64_tr_b16 v[190:191], v144 offset:0x2a00
	ds_read_b64_tr_b16 v[198:199], v144 offset:0x3200
	ds_read_b64_tr_b16 v[200:201], v144 offset:0x3a00
	s_waitcnt lgkmcnt(0)
	v_mfma_f32_32x32x16_bf16 v[0:15], v[160:163], v[194:197], v[0:15]
	v_mfma_f32_32x32x16_bf16 v[48:63], v[176:179], v[180:183], v[48:63]
	ds_read_b64_tr_b16 v[180:181], v144 offset:0x400
	ds_read_b64_tr_b16 v[182:183], v144 offset:0xc00
	v_mfma_f32_32x32x16_bf16 v[48:63], v[156:159], v[184:187], v[48:63]
	ds_read_b64_tr_b16 v[184:185], v144 offset:0x1400
	ds_read_b64_tr_b16 v[186:187], v144 offset:0x1c00
	v_mfma_f32_32x32x16_bf16 v[48:63], v[152:155], v[188:191], v[48:63]
	ds_read_b64_tr_b16 v[188:189], v144 offset:0x2400
	ds_read_b64_tr_b16 v[190:191], v144 offset:0x2c00
	ds_read_b64_tr_b16 v[194:195], v144 offset:0x3400
	ds_read_b64_tr_b16 v[196:197], v144 offset:0x3c00
	s_waitcnt lgkmcnt(0)
	v_mfma_f32_32x32x16_bf16 v[48:63], v[160:163], v[198:201], v[48:63]
	v_mfma_f32_32x32x16_bf16 v[32:47], v[176:179], v[180:183], v[32:47]
	ds_read_b64_tr_b16 v[180:181], v144 offset:0x600
	ds_read_b64_tr_b16 v[182:183], v144 offset:0xe00
	v_mfma_f32_32x32x16_bf16 v[32:47], v[156:159], v[184:187], v[32:47]
	ds_read_b64_tr_b16 v[184:185], v144 offset:0x1600
	ds_read_b64_tr_b16 v[186:187], v144 offset:0x1e00
	v_mfma_f32_32x32x16_bf16 v[32:47], v[152:155], v[188:191], v[32:47]
	ds_read_b64_tr_b16 v[188:189], v144 offset:0x2600
	ds_read_b64_tr_b16 v[190:191], v144 offset:0x2e00
	ds_read_b64_tr_b16 v[198:199], v144 offset:0x3600
	ds_read_b64_tr_b16 v[200:201], v144 offset:0x3e00
	s_waitcnt lgkmcnt(0)
	v_mfma_f32_32x32x16_bf16 v[32:47], v[160:163], v[194:197], v[32:47]
	v_mfma_f32_32x32x16_bf16 v[16:31], v[176:179], v[180:183], v[16:31]
	v_max_f32_e32 v144, v81, v81
	v_max_f32_e32 v151, v80, v80
	v_max_f32_e32 v144, v151, v144
	v_max3_f32 v144, v144, v82, v83
	v_max3_f32 v144, v144, v84, v85
	v_max3_f32 v144, v144, v86, v87
	v_max3_f32 v144, v144, v88, v89
	v_max3_f32 v144, v144, v90, v91
	v_mfma_f32_32x32x16_bf16 v[16:31], v[156:159], v[184:187], v[16:31]
	v_max3_f32 v144, v144, v92, v93
	v_max3_f32 v144, v144, v94, v95
	v_max3_f32 v144, v144, v64, v65
	v_max3_f32 v144, v144, v66, v67
	v_max3_f32 v144, v144, v68, v69
	v_max3_f32 v144, v144, v70, v71
	v_max3_f32 v144, v144, v72, v73
	v_max3_f32 v144, v144, v74, v75
	v_mfma_f32_32x32x16_bf16 v[16:31], v[152:155], v[188:191], v[16:31]
	v_max3_f32 v144, v144, v76, v77
	v_max3_f32 v144, v144, v78, v79
	v_mov_b32_e32 v151, v144
	s_nop 1
	v_permlane32_swap_b32_e32 v144, v151
	v_max_f32_e32 v151, v151, v151
	v_max_f32_e32 v144, v144, v144
	v_max_f32_e32 v144, v144, v151
	v_max_f32_e32 v151, v150, v150
	v_max_f32_e32 v151, v151, v144
	v_sub_f32_e32 v152, v144, v150
	v_mfma_f32_32x32x16_bf16 v[16:31], v[160:163], v[198:201], v[16:31]
	v_sub_f32_e32 v144, v150, v151
	v_mul_f32_e32 v144, 0x3dd53b94, v144
	v_exp_f32_e32 v144, v144
	v_cmp_ge_f32_e32 vcc, s63, v152
	s_cmp_eq_u64 vcc, exec
	s_cselect_b64 s[4:5], -1, 0
	s_waitcnt vmcnt(0)
	v_cndmask_b32_e64 v144, v144, 1.0, s[4:5]
	v_cmp_gt_f32_e32 vcc, 1.0, v144
	s_waitcnt vmcnt(0)
	s_barrier
	s_cbranch_vccz .LBB0_1106
	s_and_saveexec_b64 s[34:35], s[2:3]
	ds_write_b32 v149, v144 offset:128
	s_or_b64 exec, exec, s[34:35]
	s_waitcnt lgkmcnt(0)
	v_add_u32_e32 v164, v147, v148
	ds_read_b128 v[152:155], v164 offset:224
	ds_read_b128 v[156:159], v164 offset:192
	ds_read_b128 v[160:163], v164 offset:160
	ds_read_b128 v[176:179], v164 offset:128
	s_waitcnt lgkmcnt(3)
	v_pk_mul_f32 v[12:13], v[12:13], v[152:153]
	s_waitcnt lgkmcnt(2)
	v_pk_mul_f32 v[8:9], v[8:9], v[156:157]
	s_waitcnt lgkmcnt(1)
	v_pk_mul_f32 v[4:5], v[4:5], v[160:161]
	v_pk_mul_f32 v[14:15], v[14:15], v[154:155]
	v_pk_mul_f32 v[10:11], v[10:11], v[158:159]
	v_pk_mul_f32 v[6:7], v[6:7], v[162:163]
	s_waitcnt lgkmcnt(0)
	v_pk_mul_f32 v[2:3], v[2:3], v[178:179]
	v_pk_mul_f32 v[0:1], v[0:1], v[176:177]
	v_pk_mul_f32 v[60:61], v[60:61], v[152:153]
	v_pk_mul_f32 v[56:57], v[56:57], v[156:157]
	v_pk_mul_f32 v[52:53], v[52:53], v[160:161]
	v_pk_mul_f32 v[62:63], v[62:63], v[154:155]
	v_pk_mul_f32 v[58:59], v[58:59], v[158:159]
	v_pk_mul_f32 v[54:55], v[54:55], v[162:163]
	v_pk_mul_f32 v[50:51], v[50:51], v[178:179]
	v_pk_mul_f32 v[48:49], v[48:49], v[176:177]
	v_pk_mul_f32 v[44:45], v[44:45], v[152:153]
	v_pk_mul_f32 v[40:41], v[40:41], v[156:157]
	v_pk_mul_f32 v[36:37], v[36:37], v[160:161]
	v_pk_mul_f32 v[46:47], v[46:47], v[154:155]
	v_pk_mul_f32 v[42:43], v[42:43], v[158:159]
	v_pk_mul_f32 v[38:39], v[38:39], v[162:163]
	v_pk_mul_f32 v[34:35], v[34:35], v[178:179]
	v_pk_mul_f32 v[32:33], v[32:33], v[176:177]
	v_pk_mul_f32 v[28:29], v[28:29], v[152:153]
	v_pk_mul_f32 v[24:25], v[24:25], v[156:157]
	v_pk_mul_f32 v[20:21], v[20:21], v[160:161]
	v_pk_mul_f32 v[30:31], v[30:31], v[154:155]
	v_pk_mul_f32 v[26:27], v[26:27], v[158:159]
	v_pk_mul_f32 v[22:23], v[22:23], v[162:163]
	v_pk_mul_f32 v[18:19], v[18:19], v[178:179]
	v_pk_mul_f32 v[16:17], v[16:17], v[176:177]

	.amdhsa_kernel _Z6mk_fwd6Params
		.amdhsa_group_segment_fixed_size 0
		.amdhsa_private_segment_fixed_size 0
		.amdhsa_kernarg_size 472
		.amdhsa_user_sgpr_count 2
		.amdhsa_user_sgpr_dispatch_ptr 0
		.amdhsa_user_sgpr_queue_ptr 0
		.amdhsa_user_sgpr_kernarg_segment_ptr 1
		.amdhsa_user_sgpr_dispatch_id 0
		.amdhsa_user_sgpr_kernarg_preload_length 0
		.amdhsa_user_sgpr_kernarg_preload_offset 0
		.amdhsa_user_sgpr_private_segment_size 0
		.amdhsa_uses_dynamic_stack 0
		.amdhsa_enable_private_segment 0
		.amdhsa_system_sgpr_workgroup_id_x 1
		.amdhsa_system_sgpr_workgroup_id_y 0
		.amdhsa_system_sgpr_workgroup_id_z 0
		.amdhsa_system_sgpr_workgroup_info 0
		.amdhsa_system_vgpr_workitem_id 2
		.amdhsa_next_free_vgpr 256
		.amdhsa_next_free_sgpr 102
		.amdhsa_accum_offset 256
		.amdhsa_reserve_vcc 1
		.amdhsa_float_round_mode_32 0
		.amdhsa_float_round_mode_16_64 0
		.amdhsa_float_denorm_mode_32 3
		.amdhsa_float_denorm_mode_16_64 3
		.amdhsa_dx10_clamp 1
		.amdhsa_ieee_mode 1
		.amdhsa_fp16_overflow 0
		.amdhsa_tg_split 0
		.amdhsa_exception_fp_ieee_invalid_op 0
		.amdhsa_exception_fp_denorm_src 0
		.amdhsa_exception_fp_ieee_div_zero 0
		.amdhsa_exception_fp_ieee_overflow 0
		.amdhsa_exception_fp_ieee_underflow 0
		.amdhsa_exception_fp_ieee_inexact 0
		.amdhsa_exception_int_div_zero 0
	.end_amdhsa_kernel

amdhsa.kernels:
  - .agpr_count:     0
    .args:
      - .offset:         0
        .size:           216
        .value_kind:     by_value
      - .offset:         216
        .size:           4
        .value_kind:     hidden_block_count_x
      - .offset:         220
        .size:           4
        .value_kind:     hidden_block_count_y
      - .offset:         224
        .size:           4
        .value_kind:     hidden_block_count_z
      - .offset:         228
        .size:           2
        .value_kind:     hidden_group_size_x
      - .offset:         230
        .size:           2
        .value_kind:     hidden_group_size_y
      - .offset:         232
        .size:           2
        .value_kind:     hidden_group_size_z
      - .offset:         234
        .size:           2
        .value_kind:     hidden_remainder_x
      - .offset:         236
        .size:           2
        .value_kind:     hidden_remainder_y
      - .offset:         238
        .size:           2
        .value_kind:     hidden_remainder_z
      - .offset:         256
        .size:           8
        .value_kind:     hidden_global_offset_x
      - .offset:         264
        .size:           8
        .value_kind:     hidden_global_offset_y
      - .offset:         272
        .size:           8
        .value_kind:     hidden_global_offset_z
      - .offset:         280
        .size:           2
        .value_kind:     hidden_grid_dims
      - .offset:         304
        .size:           8
        .value_kind:     hidden_multigrid_sync_arg
      - .offset:         336
        .size:           4
        .value_kind:     hidden_dynamic_lds_size
    .group_segment_fixed_size: 0
    .kernarg_segment_align: 8
    .kernarg_segment_size: 472
    .language:       OpenCL C
    .language_version:
      - 2
      - 0
    .max_flat_workgroup_size: 512
    .name:           _Z6mk_fwd6Params
    .private_segment_fixed_size: 0
    .sgpr_count:     108
    .sgpr_spill_count: 77
    .symbol:         _Z6mk_fwd6Params.kd
    .uniform_work_group_size: 1
    .uses_dynamic_stack: false
    .vgpr_count:     256
    .vgpr_spill_count: 0
    .wavefront_size: 64
